# GEMM1/2/4 k-loops: back-edge rotated so the loop-closing barrier is the loop head (branch executes before the barrier; exit path has its own barrier copy)
# baseline (speedup 1.0000x reference)
.LBB0_282:
	v_mov_b32_e32 v129, v131
	v_lshl_add_u64 v[0:1], s[6:7], 0, v[130:131]
	v_lshl_add_u64 v[2:3], s[6:7], 0, v[128:129]
	v_readfirstlane_b32 s6, v154
	v_lshl_add_u64 v[0:1], v[0:1], 0, s[80:81]
	s_mov_b32 m0, s6
	v_readfirstlane_b32 s6, v155
	v_lshl_add_u64 v[4:5], s[8:9], 0, v[130:131]
	s_waitcnt vmcnt(4)
	s_barrier
	global_load_lds_dwordx4 v[0:1], off
	v_lshl_add_u64 v[0:1], v[2:3], 0, s[80:81]
	s_mov_b32 m0, s6
	v_readfirstlane_b32 s6, v156
	v_lshl_add_u64 v[6:7], s[8:9], 0, v[128:129]
	global_load_lds_dwordx4 v[0:1], off
	v_lshl_add_u64 v[0:1], v[4:5], 0, s[80:81]
	s_mov_b32 m0, s6
	v_readfirstlane_b32 s6, v157
	v_lshl_add_u64 v[8:9], s[10:11], 0, v[130:131]
	global_load_lds_dwordx4 v[0:1], off
	v_lshl_add_u64 v[0:1], v[6:7], 0, s[80:81]
	s_mov_b32 m0, s6
	v_readfirstlane_b32 s6, v158
	v_lshl_add_u64 v[10:11], s[10:11], 0, v[128:129]
	global_load_lds_dwordx4 v[0:1], off
	v_lshl_add_u64 v[0:1], v[8:9], 0, s[80:81]
	s_mov_b32 m0, s6
	v_readfirstlane_b32 s6, v159
	global_load_lds_dwordx4 v[0:1], off
	v_lshl_add_u64 v[0:1], v[10:11], 0, s[80:81]
	s_mov_b32 m0, s6
	v_lshl_add_u64 v[134:135], s[12:13], 0, v[130:131]
	global_load_lds_dwordx4 v[0:1], off
	s_waitcnt vmcnt(6)
	v_mov_b32_e32 v0, 0
	v_lshl_add_u64 v[132:133], s[12:13], 0, v[128:129]
	v_lshl_add_u64 v[136:137], s[0:1], 0, v[130:131]
	v_lshl_add_u64 v[138:139], s[0:1], 0, v[128:129]
	v_lshl_add_u64 v[140:141], s[4:5], 0, v[130:131]
	v_lshl_add_u64 v[142:143], s[4:5], 0, v[128:129]
	s_mov_b32 s4, -2
	s_mov_b64 s[0:1], s[28:29]
	v_mov_b32_e32 v1, v0
	v_mov_b32_e32 v2, v0
	v_mov_b32_e32 v3, v0
	v_mov_b32_e32 v4, v0
	v_mov_b32_e32 v5, v0
	v_mov_b32_e32 v6, v0
	v_mov_b32_e32 v7, v0
	v_mov_b32_e32 v8, v0
	v_mov_b32_e32 v9, v0
	v_mov_b32_e32 v10, v0
	v_mov_b32_e32 v11, v0
	v_mov_b32_e32 v12, v0
	v_mov_b32_e32 v13, v0
	v_mov_b32_e32 v14, v0
	v_mov_b32_e32 v15, v0
	v_mov_b32_e32 v16, v0
	v_mov_b32_e32 v17, v0
	v_mov_b32_e32 v18, v0
	v_mov_b32_e32 v19, v0
	v_mov_b32_e32 v20, v0
	v_mov_b32_e32 v21, v0
	v_mov_b32_e32 v22, v0
	v_mov_b32_e32 v23, v0
	v_mov_b32_e32 v24, v0
	v_mov_b32_e32 v25, v0
	v_mov_b32_e32 v26, v0
	v_mov_b32_e32 v27, v0
	v_mov_b32_e32 v28, v0
	v_mov_b32_e32 v29, v0
	v_mov_b32_e32 v30, v0
	v_mov_b32_e32 v31, v0
	v_mov_b32_e32 v32, v0
	v_mov_b32_e32 v33, v0
	v_mov_b32_e32 v34, v0
	v_mov_b32_e32 v35, v0
	v_mov_b32_e32 v36, v0
	v_mov_b32_e32 v37, v0
	v_mov_b32_e32 v38, v0
	v_mov_b32_e32 v39, v0
	v_mov_b32_e32 v40, v0
	v_mov_b32_e32 v41, v0
	v_mov_b32_e32 v42, v0
	v_mov_b32_e32 v43, v0
	v_mov_b32_e32 v44, v0
	v_mov_b32_e32 v45, v0
	v_mov_b32_e32 v46, v0
	v_mov_b32_e32 v47, v0
	v_mov_b32_e32 v48, v0
	v_mov_b32_e32 v49, v0
	v_mov_b32_e32 v50, v0
	v_mov_b32_e32 v51, v0
	v_mov_b32_e32 v52, v0
	v_mov_b32_e32 v53, v0
	v_mov_b32_e32 v54, v0
	v_mov_b32_e32 v55, v0
	v_mov_b32_e32 v56, v0
	v_mov_b32_e32 v57, v0
	v_mov_b32_e32 v58, v0
	v_mov_b32_e32 v59, v0
	v_mov_b32_e32 v60, v0
	v_mov_b32_e32 v61, v0
	v_mov_b32_e32 v62, v0
	v_mov_b32_e32 v63, v0
	v_mov_b32_e32 v64, v0
	v_mov_b32_e32 v65, v0
	v_mov_b32_e32 v66, v0
	v_mov_b32_e32 v67, v0
	v_mov_b32_e32 v68, v0
	v_mov_b32_e32 v69, v0
	v_mov_b32_e32 v70, v0
	v_mov_b32_e32 v71, v0
	v_mov_b32_e32 v72, v0
	v_mov_b32_e32 v73, v0
	v_mov_b32_e32 v74, v0
	v_mov_b32_e32 v75, v0
	v_mov_b32_e32 v76, v0
	v_mov_b32_e32 v77, v0
	v_mov_b32_e32 v78, v0
	v_mov_b32_e32 v79, v0
	v_mov_b32_e32 v80, v0
	v_mov_b32_e32 v81, v0
	v_mov_b32_e32 v82, v0
	v_mov_b32_e32 v83, v0
	v_mov_b32_e32 v84, v0
	v_mov_b32_e32 v85, v0
	v_mov_b32_e32 v86, v0
	v_mov_b32_e32 v87, v0
	v_mov_b32_e32 v88, v0
	v_mov_b32_e32 v89, v0
	v_mov_b32_e32 v90, v0
	v_mov_b32_e32 v91, v0
	v_mov_b32_e32 v92, v0
	v_mov_b32_e32 v93, v0
	v_mov_b32_e32 v94, v0
	v_mov_b32_e32 v95, v0
	v_mov_b32_e32 v96, v0
	v_mov_b32_e32 v97, v0
	v_mov_b32_e32 v98, v0
	v_mov_b32_e32 v99, v0
	v_mov_b32_e32 v100, v0
	v_mov_b32_e32 v101, v0
	v_mov_b32_e32 v102, v0
	v_mov_b32_e32 v103, v0
	v_mov_b32_e32 v104, v0
	v_mov_b32_e32 v105, v0
	v_mov_b32_e32 v106, v0
	v_mov_b32_e32 v107, v0
	v_mov_b32_e32 v108, v0
	v_mov_b32_e32 v109, v0
	v_mov_b32_e32 v110, v0
	v_mov_b32_e32 v111, v0
	v_mov_b32_e32 v112, v0
	v_mov_b32_e32 v113, v0
	v_mov_b32_e32 v114, v0
	v_mov_b32_e32 v115, v0
	v_mov_b32_e32 v116, v0
	v_mov_b32_e32 v117, v0
	v_mov_b32_e32 v118, v0
	v_mov_b32_e32 v119, v0
	v_mov_b32_e32 v120, v0
	v_mov_b32_e32 v121, v0
	v_mov_b32_e32 v122, v0
	v_mov_b32_e32 v123, v0
	v_mov_b32_e32 v124, v0
	v_mov_b32_e32 v125, v0
	v_mov_b32_e32 v126, v0
	v_mov_b32_e32 v127, v0
.Lmy_rot_0:
	s_barrier
.LBB0_283:
	ds_read_b128 v[170:173], v160
	ds_read_b128 v[174:177], v160 offset:1024
	ds_read_b128 v[178:181], v160 offset:2048
	ds_read_b128 v[182:185], v160 offset:3072
	v_add_u32_e32 v167, 0xc000, v148
	v_lshl_add_u64 v[222:223], s[0:1], 0, v[140:141]
	v_readfirstlane_b32 s5, v167
	v_add_u32_e32 v129, s61, v145
	v_add_u32_e32 v165, s63, v145
	v_add_u32_e32 v166, s64, v145
	v_lshl_add_u64 v[168:169], v[222:223], 0, s[82:83]
	s_mov_b32 m0, s5
	ds_read_b128 v[186:189], v161
	ds_read_b128 v[190:193], v161 offset:1024
	ds_read_b128 v[194:197], v129
	ds_read_b128 v[198:201], v129 offset:1024
	ds_read_b128 v[202:205], v165
	ds_read_b128 v[206:209], v165 offset:1024
	ds_read_b128 v[210:213], v166
	ds_read_b128 v[214:217], v166 offset:1024
	global_load_lds_dwordx4 v[168:169], off
	v_add_u32_e32 v168, 0xe000, v148
	v_lshl_add_u64 v[238:239], s[0:1], 0, v[142:143]
	v_readfirstlane_b32 s5, v168
	v_lshl_add_u64 v[218:219], v[238:239], 0, s[82:83]
	s_mov_b32 m0, s5
	s_nop 0
	global_load_lds_dwordx4 v[218:219], off
	s_waitcnt lgkmcnt(8)
	s_barrier
	s_waitcnt lgkmcnt(0)
	s_setprio 1
	v_mfma_f32_16x16x32_bf16 v[124:127], v[186:189], v[170:173], v[124:127]
	v_mfma_f32_16x16x32_bf16 v[120:123], v[186:189], v[178:181], v[120:123]
	v_mfma_f32_16x16x32_bf16 v[116:119], v[194:197], v[170:173], v[116:119]
	v_mfma_f32_16x16x32_bf16 v[112:115], v[194:197], v[178:181], v[112:115]
	v_mfma_f32_16x16x32_bf16 v[108:111], v[202:205], v[170:173], v[108:111]
	v_mfma_f32_16x16x32_bf16 v[104:107], v[202:205], v[178:181], v[104:107]
	v_mfma_f32_16x16x32_bf16 v[100:103], v[210:213], v[170:173], v[100:103]
	v_mfma_f32_16x16x32_bf16 v[96:99], v[210:213], v[178:181], v[96:99]
	v_mfma_f32_16x16x32_bf16 v[124:127], v[190:193], v[174:177], v[124:127]
	v_mfma_f32_16x16x32_bf16 v[120:123], v[190:193], v[182:185], v[120:123]
	v_mfma_f32_16x16x32_bf16 v[116:119], v[198:201], v[174:177], v[116:119]
	v_mfma_f32_16x16x32_bf16 v[112:115], v[198:201], v[182:185], v[112:115]
	v_mfma_f32_16x16x32_bf16 v[108:111], v[206:209], v[174:177], v[108:111]
	v_mfma_f32_16x16x32_bf16 v[104:107], v[206:209], v[182:185], v[104:107]
	v_mfma_f32_16x16x32_bf16 v[100:103], v[214:217], v[174:177], v[100:103]
	v_mfma_f32_16x16x32_bf16 v[96:99], v[214:217], v[182:185], v[96:99]
	s_setprio 0
	s_barrier
	v_lshl_add_u64 v[240:241], s[0:1], 0, v[136:137]
	v_readfirstlane_b32 s5, v146
	v_lshl_add_u64 v[242:243], v[240:241], 0, s[84:85]
	s_mov_b32 m0, s5
	ds_read_b128 v[218:221], v162
	ds_read_b128 v[226:229], v162 offset:1024
	ds_read_b128 v[230:233], v162 offset:2048
	ds_read_b128 v[234:237], v162 offset:3072
	global_load_lds_dwordx4 v[242:243], off
	v_lshl_add_u64 v[242:243], s[0:1], 0, v[138:139]
	v_readfirstlane_b32 s5, v147
	v_lshl_add_u64 v[244:245], v[242:243], 0, s[84:85]
	s_mov_b32 m0, s5
	s_nop 0
	global_load_lds_dwordx4 v[244:245], off
	s_barrier
	s_waitcnt lgkmcnt(0)
	s_setprio 1
	v_mfma_f32_16x16x32_bf16 v[92:95], v[186:189], v[218:221], v[92:95]
	v_mfma_f32_16x16x32_bf16 v[88:91], v[186:189], v[230:233], v[88:91]
	v_mfma_f32_16x16x32_bf16 v[84:87], v[194:197], v[218:221], v[84:87]
	v_mfma_f32_16x16x32_bf16 v[80:83], v[194:197], v[230:233], v[80:83]
	v_mfma_f32_16x16x32_bf16 v[76:79], v[202:205], v[218:221], v[76:79]
	v_mfma_f32_16x16x32_bf16 v[72:75], v[202:205], v[230:233], v[72:75]
	v_mfma_f32_16x16x32_bf16 v[68:71], v[210:213], v[218:221], v[68:71]
	v_mfma_f32_16x16x32_bf16 v[64:67], v[210:213], v[230:233], v[64:67]
	v_mfma_f32_16x16x32_bf16 v[92:95], v[190:193], v[226:229], v[92:95]
	v_mfma_f32_16x16x32_bf16 v[88:91], v[190:193], v[234:237], v[88:91]
	v_mfma_f32_16x16x32_bf16 v[84:87], v[198:201], v[226:229], v[84:87]
	v_mfma_f32_16x16x32_bf16 v[80:83], v[198:201], v[234:237], v[80:83]
	v_mfma_f32_16x16x32_bf16 v[76:79], v[206:209], v[226:229], v[76:79]
	v_mfma_f32_16x16x32_bf16 v[72:75], v[206:209], v[234:237], v[72:75]
	v_mfma_f32_16x16x32_bf16 v[68:71], v[214:217], v[226:229], v[68:71]
	v_mfma_f32_16x16x32_bf16 v[64:67], v[214:217], v[234:237], v[64:67]
	s_setprio 0
	v_readfirstlane_b32 s5, v148
	v_lshl_add_u64 v[244:245], v[222:223], 0, s[86:87]
	s_mov_b32 m0, s5
	v_readfirstlane_b32 s5, v149
	s_barrier
	ds_read_b128 v[186:189], v161 offset:16384
	ds_read_b128 v[190:193], v161 offset:17408
	ds_read_b128 v[194:197], v129 offset:16384
	ds_read_b128 v[198:201], v129 offset:17408
	ds_read_b128 v[202:205], v165 offset:16384
	ds_read_b128 v[206:209], v165 offset:17408
	ds_read_b128 v[210:213], v166 offset:16384
	ds_read_b128 v[214:217], v166 offset:17408
	global_load_lds_dwordx4 v[244:245], off
	v_lshl_add_u64 v[244:245], v[238:239], 0, s[86:87]
	s_mov_b32 m0, s5
	s_nop 0
	global_load_lds_dwordx4 v[244:245], off
	s_barrier
	s_waitcnt lgkmcnt(0)
	s_setprio 1
	v_mfma_f32_16x16x32_bf16 v[60:63], v[186:189], v[170:173], v[60:63]
	v_mfma_f32_16x16x32_bf16 v[56:59], v[186:189], v[178:181], v[56:59]
	v_mfma_f32_16x16x32_bf16 v[52:55], v[194:197], v[170:173], v[52:55]
	v_mfma_f32_16x16x32_bf16 v[48:51], v[194:197], v[178:181], v[48:51]
	v_mfma_f32_16x16x32_bf16 v[44:47], v[202:205], v[170:173], v[44:47]
	v_mfma_f32_16x16x32_bf16 v[40:43], v[202:205], v[178:181], v[40:43]
	v_mfma_f32_16x16x32_bf16 v[36:39], v[210:213], v[170:173], v[36:39]
	v_mfma_f32_16x16x32_bf16 v[32:35], v[210:213], v[178:181], v[32:35]
	v_mfma_f32_16x16x32_bf16 v[60:63], v[190:193], v[174:177], v[60:63]
	v_mfma_f32_16x16x32_bf16 v[56:59], v[190:193], v[182:185], v[56:59]
	v_mfma_f32_16x16x32_bf16 v[52:55], v[198:201], v[174:177], v[52:55]
	v_mfma_f32_16x16x32_bf16 v[48:51], v[198:201], v[182:185], v[48:51]
	v_mfma_f32_16x16x32_bf16 v[44:47], v[206:209], v[174:177], v[44:47]
	v_mfma_f32_16x16x32_bf16 v[40:43], v[206:209], v[182:185], v[40:43]
	v_mfma_f32_16x16x32_bf16 v[36:39], v[214:217], v[174:177], v[36:39]
	v_mfma_f32_16x16x32_bf16 v[32:35], v[214:217], v[182:185], v[32:35]
	s_setprio 0
	s_barrier
	v_readfirstlane_b32 s5, v150
	v_lshl_add_u64 v[170:171], v[240:241], 0, s[88:89]
	s_mov_b32 m0, s5
	v_readfirstlane_b32 s5, v151
	global_load_lds_dwordx4 v[170:171], off
	v_lshl_add_u64 v[170:171], v[242:243], 0, s[88:89]
	s_mov_b32 m0, s5
	s_nop 0
	global_load_lds_dwordx4 v[170:171], off
	s_waitcnt vmcnt(6)
	s_barrier
	s_setprio 1
	v_mfma_f32_16x16x32_bf16 v[28:31], v[186:189], v[218:221], v[28:31]
	v_mfma_f32_16x16x32_bf16 v[24:27], v[186:189], v[230:233], v[24:27]
	v_mfma_f32_16x16x32_bf16 v[20:23], v[194:197], v[218:221], v[20:23]
	v_mfma_f32_16x16x32_bf16 v[16:19], v[194:197], v[230:233], v[16:19]
	v_mfma_f32_16x16x32_bf16 v[12:15], v[202:205], v[218:221], v[12:15]
	v_mfma_f32_16x16x32_bf16 v[8:11], v[202:205], v[230:233], v[8:11]
	v_mfma_f32_16x16x32_bf16 v[4:7], v[210:213], v[218:221], v[4:7]
	v_mfma_f32_16x16x32_bf16 v[0:3], v[210:213], v[230:233], v[0:3]
	v_mfma_f32_16x16x32_bf16 v[28:31], v[190:193], v[226:229], v[28:31]
	v_mfma_f32_16x16x32_bf16 v[24:27], v[190:193], v[234:237], v[24:27]
	v_mfma_f32_16x16x32_bf16 v[20:23], v[198:201], v[226:229], v[20:23]
	v_mfma_f32_16x16x32_bf16 v[16:19], v[198:201], v[234:237], v[16:19]
	v_mfma_f32_16x16x32_bf16 v[12:15], v[206:209], v[226:229], v[12:15]
	v_mfma_f32_16x16x32_bf16 v[8:11], v[206:209], v[234:237], v[8:11]
	v_mfma_f32_16x16x32_bf16 v[4:7], v[214:217], v[226:229], v[4:7]
	v_mfma_f32_16x16x32_bf16 v[0:3], v[214:217], v[234:237], v[0:3]
	s_setprio 0
	s_barrier
	ds_read_b128 v[170:173], v163
	ds_read_b128 v[174:177], v163 offset:1024
	ds_read_b128 v[178:181], v163 offset:2048
	ds_read_b128 v[182:185], v163 offset:3072
	v_readfirstlane_b32 s5, v152
	v_lshl_add_u64 v[218:219], v[222:223], 0, s[90:91]
	s_mov_b32 m0, s5
	v_readfirstlane_b32 s5, v153
	ds_read_b128 v[186:189], v161 offset:32768
	ds_read_b128 v[190:193], v161 offset:33792
	ds_read_b128 v[194:197], v129 offset:32768
	ds_read_b128 v[198:201], v129 offset:33792
	ds_read_b128 v[202:205], v165 offset:32768
	ds_read_b128 v[206:209], v165 offset:33792
	ds_read_b128 v[210:213], v166 offset:32768
	ds_read_b128 v[214:217], v166 offset:33792
	global_load_lds_dwordx4 v[218:219], off
	v_lshl_add_u64 v[218:219], v[238:239], 0, s[90:91]
	s_mov_b32 m0, s5
	s_nop 0
	global_load_lds_dwordx4 v[218:219], off
	s_waitcnt lgkmcnt(8)
	s_barrier
	s_waitcnt lgkmcnt(0)
	s_setprio 1
	v_mfma_f32_16x16x32_bf16 v[124:127], v[186:189], v[170:173], v[124:127]
	v_mfma_f32_16x16x32_bf16 v[120:123], v[186:189], v[178:181], v[120:123]
	v_mfma_f32_16x16x32_bf16 v[116:119], v[194:197], v[170:173], v[116:119]
	v_mfma_f32_16x16x32_bf16 v[112:115], v[194:197], v[178:181], v[112:115]
	v_mfma_f32_16x16x32_bf16 v[108:111], v[202:205], v[170:173], v[108:111]
	v_mfma_f32_16x16x32_bf16 v[104:107], v[202:205], v[178:181], v[104:107]
	v_mfma_f32_16x16x32_bf16 v[100:103], v[210:213], v[170:173], v[100:103]
	v_mfma_f32_16x16x32_bf16 v[96:99], v[210:213], v[178:181], v[96:99]
	v_mfma_f32_16x16x32_bf16 v[124:127], v[190:193], v[174:177], v[124:127]
	v_mfma_f32_16x16x32_bf16 v[120:123], v[190:193], v[182:185], v[120:123]
	v_mfma_f32_16x16x32_bf16 v[116:119], v[198:201], v[174:177], v[116:119]
	v_mfma_f32_16x16x32_bf16 v[112:115], v[198:201], v[182:185], v[112:115]
	v_mfma_f32_16x16x32_bf16 v[108:111], v[206:209], v[174:177], v[108:111]
	v_mfma_f32_16x16x32_bf16 v[104:107], v[206:209], v[182:185], v[104:107]
	v_mfma_f32_16x16x32_bf16 v[100:103], v[214:217], v[174:177], v[100:103]
	v_mfma_f32_16x16x32_bf16 v[96:99], v[214:217], v[182:185], v[96:99]
	s_setprio 0
	s_barrier
	v_readfirstlane_b32 s5, v154
	v_lshl_add_u64 v[244:245], v[240:241], 0, s[92:93]
	s_mov_b32 m0, s5
	v_readfirstlane_b32 s5, v155
	ds_read_b128 v[218:221], v164
	ds_read_b128 v[226:229], v164 offset:1024
	ds_read_b128 v[230:233], v164 offset:2048
	ds_read_b128 v[234:237], v164 offset:3072
	global_load_lds_dwordx4 v[244:245], off
	v_lshl_add_u64 v[244:245], v[242:243], 0, s[92:93]
	s_mov_b32 m0, s5
	s_nop 0
	global_load_lds_dwordx4 v[244:245], off
	s_barrier
	s_waitcnt lgkmcnt(0)
	s_setprio 1
	v_mfma_f32_16x16x32_bf16 v[92:95], v[186:189], v[218:221], v[92:95]
	v_mfma_f32_16x16x32_bf16 v[88:91], v[186:189], v[230:233], v[88:91]
	v_mfma_f32_16x16x32_bf16 v[84:87], v[194:197], v[218:221], v[84:87]
	v_mfma_f32_16x16x32_bf16 v[80:83], v[194:197], v[230:233], v[80:83]
	v_mfma_f32_16x16x32_bf16 v[76:79], v[202:205], v[218:221], v[76:79]
	v_mfma_f32_16x16x32_bf16 v[72:75], v[202:205], v[230:233], v[72:75]
	v_mfma_f32_16x16x32_bf16 v[68:71], v[210:213], v[218:221], v[68:71]
	v_mfma_f32_16x16x32_bf16 v[64:67], v[210:213], v[230:233], v[64:67]
	v_mfma_f32_16x16x32_bf16 v[92:95], v[190:193], v[226:229], v[92:95]
	v_mfma_f32_16x16x32_bf16 v[88:91], v[190:193], v[234:237], v[88:91]
	v_mfma_f32_16x16x32_bf16 v[84:87], v[198:201], v[226:229], v[84:87]
	v_mfma_f32_16x16x32_bf16 v[80:83], v[198:201], v[234:237], v[80:83]
	v_mfma_f32_16x16x32_bf16 v[76:79], v[206:209], v[226:229], v[76:79]
	v_mfma_f32_16x16x32_bf16 v[72:75], v[206:209], v[234:237], v[72:75]
	v_mfma_f32_16x16x32_bf16 v[68:71], v[214:217], v[226:229], v[68:71]
	v_mfma_f32_16x16x32_bf16 v[64:67], v[214:217], v[234:237], v[64:67]
	s_setprio 0
	v_readfirstlane_b32 s5, v156
	v_lshl_add_u64 v[222:223], v[222:223], 0, s[94:95]
	s_mov_b32 m0, s5
	v_readfirstlane_b32 s5, v157
	s_barrier
	ds_read_b128 v[186:189], v161 offset:49152
	ds_read_b128 v[190:193], v161 offset:50176
	ds_read_b128 v[194:197], v129 offset:49152
	ds_read_b128 v[198:201], v129 offset:50176
	ds_read_b128 v[202:205], v165 offset:49152
	ds_read_b128 v[206:209], v165 offset:50176
	ds_read_b128 v[210:213], v166 offset:49152
	ds_read_b128 v[214:217], v166 offset:50176
	global_load_lds_dwordx4 v[222:223], off
	v_lshl_add_u64 v[222:223], v[238:239], 0, s[94:95]
	s_mov_b32 m0, s5
	s_nop 0
	global_load_lds_dwordx4 v[222:223], off
	s_barrier
	s_waitcnt lgkmcnt(0)
	s_setprio 1
	v_mfma_f32_16x16x32_bf16 v[60:63], v[186:189], v[170:173], v[60:63]
	v_mfma_f32_16x16x32_bf16 v[56:59], v[186:189], v[178:181], v[56:59]
	v_mfma_f32_16x16x32_bf16 v[52:55], v[194:197], v[170:173], v[52:55]
	v_mfma_f32_16x16x32_bf16 v[48:51], v[194:197], v[178:181], v[48:51]
	v_mfma_f32_16x16x32_bf16 v[44:47], v[202:205], v[170:173], v[44:47]
	v_mfma_f32_16x16x32_bf16 v[40:43], v[202:205], v[178:181], v[40:43]
	v_mfma_f32_16x16x32_bf16 v[36:39], v[210:213], v[170:173], v[36:39]
	v_mfma_f32_16x16x32_bf16 v[32:35], v[210:213], v[178:181], v[32:35]
	v_mfma_f32_16x16x32_bf16 v[60:63], v[190:193], v[174:177], v[60:63]
	v_mfma_f32_16x16x32_bf16 v[56:59], v[190:193], v[182:185], v[56:59]
	v_mfma_f32_16x16x32_bf16 v[52:55], v[198:201], v[174:177], v[52:55]
	v_mfma_f32_16x16x32_bf16 v[48:51], v[198:201], v[182:185], v[48:51]
	v_mfma_f32_16x16x32_bf16 v[44:47], v[206:209], v[174:177], v[44:47]
	v_mfma_f32_16x16x32_bf16 v[40:43], v[206:209], v[182:185], v[40:43]
	v_mfma_f32_16x16x32_bf16 v[36:39], v[214:217], v[174:177], v[36:39]
	v_mfma_f32_16x16x32_bf16 v[32:35], v[214:217], v[182:185], v[32:35]
	s_setprio 0
	s_barrier
	v_readfirstlane_b32 s5, v158
	v_lshl_add_u64 v[170:171], v[240:241], 0, s[96:97]
	s_mov_b32 m0, s5
	v_readfirstlane_b32 s5, v159
	global_load_lds_dwordx4 v[170:171], off
	v_lshl_add_u64 v[170:171], v[242:243], 0, s[96:97]
	s_mov_b32 m0, s5
	s_nop 0
	global_load_lds_dwordx4 v[170:171], off
	s_waitcnt vmcnt(6)
	s_barrier
	s_setprio 1
	v_mfma_f32_16x16x32_bf16 v[28:31], v[186:189], v[218:221], v[28:31]
	v_mfma_f32_16x16x32_bf16 v[24:27], v[186:189], v[230:233], v[24:27]
	v_mfma_f32_16x16x32_bf16 v[20:23], v[194:197], v[218:221], v[20:23]
	v_mfma_f32_16x16x32_bf16 v[16:19], v[194:197], v[230:233], v[16:19]
	v_mfma_f32_16x16x32_bf16 v[12:15], v[202:205], v[218:221], v[12:15]
	v_mfma_f32_16x16x32_bf16 v[8:11], v[202:205], v[230:233], v[8:11]
	v_mfma_f32_16x16x32_bf16 v[4:7], v[210:213], v[218:221], v[4:7]
	v_mfma_f32_16x16x32_bf16 v[0:3], v[210:213], v[230:233], v[0:3]
	v_mfma_f32_16x16x32_bf16 v[28:31], v[190:193], v[226:229], v[28:31]
	v_mfma_f32_16x16x32_bf16 v[24:27], v[190:193], v[234:237], v[24:27]
	v_mfma_f32_16x16x32_bf16 v[20:23], v[198:201], v[226:229], v[20:23]
	v_mfma_f32_16x16x32_bf16 v[16:19], v[198:201], v[234:237], v[16:19]
	v_mfma_f32_16x16x32_bf16 v[12:15], v[206:209], v[226:229], v[12:15]
	v_mfma_f32_16x16x32_bf16 v[8:11], v[206:209], v[234:237], v[8:11]
	v_mfma_f32_16x16x32_bf16 v[4:7], v[214:217], v[226:229], v[4:7]
	v_mfma_f32_16x16x32_bf16 v[0:3], v[214:217], v[234:237], v[0:3]
	s_setprio 0
	s_add_i32 s4, s4, 2
	s_add_u32 s0, s0, 0x100
	s_addc_u32 s1, s1, 0
	s_cmp_lt_u32 s4, 28
	s_cbranch_scc1 .Lmy_rot_0
	s_barrier
	v_readfirstlane_b32 s0, v167
	v_lshl_add_u64 v[134:135], v[134:135], 0, s[34:35]
	s_mov_b32 m0, s0
	v_readfirstlane_b32 s0, v168
	ds_read_b128 v[136:139], v160
	ds_read_b128 v[140:143], v160 offset:1024
	ds_read_b128 v[170:173], v160 offset:2048
	ds_read_b128 v[174:177], v160 offset:3072
	ds_read_b128 v[178:181], v161
	ds_read_b128 v[182:185], v161 offset:1024
	ds_read_b128 v[186:189], v129
	ds_read_b128 v[190:193], v129 offset:1024
	ds_read_b128 v[194:197], v165
	ds_read_b128 v[198:201], v165 offset:1024
	ds_read_b128 v[202:205], v166
	ds_read_b128 v[206:209], v166 offset:1024
	global_load_lds_dwordx4 v[134:135], off
	v_lshl_add_u64 v[132:133], v[132:133], 0, s[34:35]
	s_mov_b32 m0, s0
	s_nop 0
	global_load_lds_dwordx4 v[132:133], off
	s_barrier
	s_waitcnt lgkmcnt(0)
	s_setprio 1
	v_mfma_f32_16x16x32_bf16 v[124:127], v[178:181], v[136:139], v[124:127]
	v_mfma_f32_16x16x32_bf16 v[120:123], v[178:181], v[170:173], v[120:123]
	v_mfma_f32_16x16x32_bf16 v[116:119], v[186:189], v[136:139], v[116:119]
	v_mfma_f32_16x16x32_bf16 v[112:115], v[186:189], v[170:173], v[112:115]
	v_mfma_f32_16x16x32_bf16 v[124:127], v[182:185], v[140:143], v[124:127]
	v_mfma_f32_16x16x32_bf16 v[120:123], v[182:185], v[174:177], v[120:123]
	v_mfma_f32_16x16x32_bf16 v[116:119], v[190:193], v[140:143], v[116:119]
	v_mfma_f32_16x16x32_bf16 v[112:115], v[190:193], v[174:177], v[112:115]
	v_mfma_f32_16x16x32_bf16 v[108:111], v[194:197], v[136:139], v[108:111]
	v_mfma_f32_16x16x32_bf16 v[104:107], v[194:197], v[170:173], v[104:107]
	v_mfma_f32_16x16x32_bf16 v[100:103], v[202:205], v[136:139], v[100:103]
	v_mfma_f32_16x16x32_bf16 v[96:99], v[202:205], v[170:173], v[96:99]
	v_mfma_f32_16x16x32_bf16 v[132:135], v[198:201], v[140:143], v[108:111]
	v_mfma_f32_16x16x32_bf16 v[210:213], v[198:201], v[174:177], v[104:107]
	v_mfma_f32_16x16x32_bf16 v[214:217], v[206:209], v[140:143], v[100:103]
	v_mfma_f32_16x16x32_bf16 v[218:221], v[206:209], v[174:177], v[96:99]
	s_setprio 0
	s_barrier
	s_nop 1
	ds_read_b128 v[96:99], v162
	ds_read_b128 v[100:103], v162 offset:1024
	ds_read_b128 v[104:107], v162 offset:2048
	ds_read_b128 v[108:111], v162 offset:3072
	s_barrier
	s_waitcnt lgkmcnt(0)
	s_setprio 1
	v_mfma_f32_16x16x32_bf16 v[92:95], v[178:181], v[96:99], v[92:95]
	v_mfma_f32_16x16x32_bf16 v[88:91], v[178:181], v[104:107], v[88:91]
	v_mfma_f32_16x16x32_bf16 v[84:87], v[186:189], v[96:99], v[84:87]
	v_mfma_f32_16x16x32_bf16 v[80:83], v[186:189], v[104:107], v[80:83]
	v_mfma_f32_16x16x32_bf16 v[92:95], v[182:185], v[100:103], v[92:95]
	v_mfma_f32_16x16x32_bf16 v[88:91], v[182:185], v[108:111], v[88:91]
	v_mfma_f32_16x16x32_bf16 v[84:87], v[190:193], v[100:103], v[84:87]
	v_mfma_f32_16x16x32_bf16 v[80:83], v[190:193], v[108:111], v[80:83]
	v_mfma_f32_16x16x32_bf16 v[76:79], v[194:197], v[96:99], v[76:79]
	v_mfma_f32_16x16x32_bf16 v[72:75], v[194:197], v[104:107], v[72:75]
	v_mfma_f32_16x16x32_bf16 v[68:71], v[202:205], v[96:99], v[68:71]
	v_mfma_f32_16x16x32_bf16 v[64:67], v[202:205], v[104:107], v[64:67]
	v_mfma_f32_16x16x32_bf16 v[178:181], v[198:201], v[100:103], v[76:79]
	v_mfma_f32_16x16x32_bf16 v[182:185], v[198:201], v[108:111], v[72:75]
	v_mfma_f32_16x16x32_bf16 v[186:189], v[206:209], v[100:103], v[68:71]
	v_mfma_f32_16x16x32_bf16 v[190:193], v[206:209], v[108:111], v[64:67]
	s_setprio 0
	s_barrier
	s_nop 1
	ds_read_b128 v[64:67], v161 offset:16384
	ds_read_b128 v[68:71], v161 offset:17408
	ds_read_b128 v[72:75], v129 offset:16384
	ds_read_b128 v[76:79], v129 offset:17408
	ds_read_b128 v[194:197], v165 offset:16384
	ds_read_b128 v[198:201], v165 offset:17408
	ds_read_b128 v[202:205], v166 offset:16384
	ds_read_b128 v[206:209], v166 offset:17408
	s_waitcnt vmcnt(4)
	s_barrier
	s_waitcnt lgkmcnt(0)
	s_setprio 1
	v_mfma_f32_16x16x32_bf16 v[60:63], v[64:67], v[136:139], v[60:63]
	v_mfma_f32_16x16x32_bf16 v[56:59], v[64:67], v[170:173], v[56:59]
	v_mfma_f32_16x16x32_bf16 v[52:55], v[72:75], v[136:139], v[52:55]
	v_mfma_f32_16x16x32_bf16 v[48:51], v[72:75], v[170:173], v[48:51]
	v_mfma_f32_16x16x32_bf16 v[60:63], v[68:71], v[140:143], v[60:63]
	v_mfma_f32_16x16x32_bf16 v[56:59], v[68:71], v[174:177], v[56:59]
	v_mfma_f32_16x16x32_bf16 v[52:55], v[76:79], v[140:143], v[52:55]
	v_mfma_f32_16x16x32_bf16 v[48:51], v[76:79], v[174:177], v[48:51]
	v_mfma_f32_16x16x32_bf16 v[44:47], v[194:197], v[136:139], v[44:47]
	v_mfma_f32_16x16x32_bf16 v[40:43], v[194:197], v[170:173], v[40:43]
	v_mfma_f32_16x16x32_bf16 v[36:39], v[202:205], v[136:139], v[36:39]
	v_mfma_f32_16x16x32_bf16 v[32:35], v[202:205], v[170:173], v[32:35]
	v_mfma_f32_16x16x32_bf16 v[226:229], v[198:201], v[140:143], v[44:47]
	v_mfma_f32_16x16x32_bf16 v[230:233], v[198:201], v[174:177], v[40:43]
	v_mfma_f32_16x16x32_bf16 v[136:139], v[206:209], v[140:143], v[36:39]
	v_mfma_f32_16x16x32_bf16 v[140:143], v[206:209], v[174:177], v[32:35]
	s_setprio 0
	s_setprio 1
	v_mfma_f32_16x16x32_bf16 v[28:31], v[64:67], v[96:99], v[28:31]
	v_mfma_f32_16x16x32_bf16 v[24:27], v[64:67], v[104:107], v[24:27]
	v_mfma_f32_16x16x32_bf16 v[20:23], v[72:75], v[96:99], v[20:23]
	v_mfma_f32_16x16x32_bf16 v[16:19], v[72:75], v[104:107], v[16:19]
	v_mfma_f32_16x16x32_bf16 v[28:31], v[68:71], v[100:103], v[28:31]
	v_mfma_f32_16x16x32_bf16 v[24:27], v[68:71], v[108:111], v[24:27]
	v_mfma_f32_16x16x32_bf16 v[20:23], v[76:79], v[100:103], v[20:23]
	v_mfma_f32_16x16x32_bf16 v[16:19], v[76:79], v[108:111], v[16:19]
	v_mfma_f32_16x16x32_bf16 v[12:15], v[194:197], v[96:99], v[12:15]
	v_mfma_f32_16x16x32_bf16 v[8:11], v[194:197], v[104:107], v[8:11]
	v_mfma_f32_16x16x32_bf16 v[4:7], v[202:205], v[96:99], v[4:7]
	v_mfma_f32_16x16x32_bf16 v[0:3], v[202:205], v[104:107], v[0:3]
	v_mfma_f32_16x16x32_bf16 v[168:171], v[198:201], v[100:103], v[12:15]
	v_mfma_f32_16x16x32_bf16 v[172:175], v[198:201], v[108:111], v[8:11]
	v_mfma_f32_16x16x32_bf16 v[194:197], v[206:209], v[100:103], v[4:7]
	v_mfma_f32_16x16x32_bf16 v[198:201], v[206:209], v[108:111], v[0:3]
	s_setprio 0
	s_barrier
	s_nop 1
	ds_read_b128 v[0:3], v163
	ds_read_b128 v[4:7], v163 offset:1024
	ds_read_b128 v[202:205], v163 offset:2048
	ds_read_b128 v[206:209], v163 offset:3072
	ds_read_b128 v[8:11], v161 offset:32768
	ds_read_b128 v[12:15], v161 offset:33792
	ds_read_b128 v[32:35], v129 offset:32768
	ds_read_b128 v[36:39], v129 offset:33792
	ds_read_b128 v[40:43], v165 offset:32768
	ds_read_b128 v[44:47], v165 offset:33792
	ds_read_b128 v[234:237], v166 offset:32768
	ds_read_b128 v[238:241], v166 offset:33792
	s_waitcnt vmcnt(2)
	s_barrier
	s_waitcnt lgkmcnt(0)
	s_setprio 1
	v_mfma_f32_16x16x32_bf16 v[64:67], v[8:11], v[0:3], v[124:127]
	v_mfma_f32_16x16x32_bf16 v[104:107], v[12:15], v[4:7], v[64:67]
	v_mfma_f32_16x16x32_bf16 v[64:67], v[8:11], v[202:205], v[120:123]
	v_mfma_f32_16x16x32_bf16 v[108:111], v[12:15], v[206:209], v[64:67]
	v_mfma_f32_16x16x32_bf16 v[64:67], v[32:35], v[0:3], v[116:119]
	v_mfma_f32_16x16x32_bf16 v[96:99], v[36:39], v[4:7], v[64:67]
	v_mfma_f32_16x16x32_bf16 v[64:67], v[32:35], v[202:205], v[112:115]
	v_mfma_f32_16x16x32_bf16 v[100:103], v[36:39], v[206:209], v[64:67]
	v_mfma_f32_16x16x32_bf16 v[64:67], v[40:43], v[0:3], v[132:135]
	v_mfma_f32_16x16x32_bf16 v[72:75], v[44:47], v[4:7], v[64:67]
	v_mfma_f32_16x16x32_bf16 v[64:67], v[40:43], v[202:205], v[210:213]
	v_mfma_f32_16x16x32_bf16 v[76:79], v[44:47], v[206:209], v[64:67]
	v_mfma_f32_16x16x32_bf16 v[64:67], v[234:237], v[0:3], v[214:217]
	v_mfma_f32_16x16x32_bf16 v[68:71], v[234:237], v[202:205], v[218:221]
	v_mfma_f32_16x16x32_bf16 v[64:67], v[238:241], v[4:7], v[64:67]
	v_mfma_f32_16x16x32_bf16 v[68:71], v[238:241], v[206:209], v[68:71]
	s_setprio 0
	s_barrier
	ds_read_b128 v[132:135], v164
	ds_read_b128 v[210:213], v164 offset:1024
	ds_read_b128 v[214:217], v164 offset:2048
	ds_read_b128 v[218:221], v164 offset:3072
	s_waitcnt vmcnt(0)
	s_barrier
	s_waitcnt lgkmcnt(0)
	s_setprio 1
	v_mfma_f32_16x16x32_bf16 v[92:95], v[8:11], v[132:135], v[92:95]
	v_mfma_f32_16x16x32_bf16 v[8:11], v[8:11], v[214:217], v[88:91]
	v_mfma_f32_16x16x32_bf16 v[124:127], v[12:15], v[218:221], v[8:11]
	v_mfma_f32_16x16x32_bf16 v[8:11], v[32:35], v[132:135], v[84:87]
	v_mfma_f32_16x16x32_bf16 v[112:115], v[36:39], v[210:213], v[8:11]
	v_mfma_f32_16x16x32_bf16 v[8:11], v[32:35], v[214:217], v[80:83]
	v_mfma_f32_16x16x32_bf16 v[116:119], v[36:39], v[218:221], v[8:11]
	v_mfma_f32_16x16x32_bf16 v[8:11], v[40:43], v[132:135], v[178:181]
	v_mfma_f32_16x16x32_bf16 v[88:91], v[44:47], v[210:213], v[8:11]
	v_mfma_f32_16x16x32_bf16 v[8:11], v[40:43], v[214:217], v[182:185]
	v_mfma_f32_16x16x32_bf16 v[120:123], v[12:15], v[210:213], v[92:95]
	v_mfma_f32_16x16x32_bf16 v[92:95], v[44:47], v[218:221], v[8:11]
	v_mfma_f32_16x16x32_bf16 v[8:11], v[234:237], v[132:135], v[186:189]
	v_mfma_f32_16x16x32_bf16 v[80:83], v[238:241], v[210:213], v[8:11]
	v_mfma_f32_16x16x32_bf16 v[8:11], v[234:237], v[214:217], v[190:193]
	v_mfma_f32_16x16x32_bf16 v[84:87], v[238:241], v[218:221], v[8:11]
	s_setprio 0
	s_barrier
	ds_read_b128 v[176:179], v161 offset:49152
	ds_read_b128 v[180:183], v161 offset:50176
	ds_read_b128 v[184:187], v129 offset:49152
	ds_read_b128 v[188:191], v129 offset:50176
	ds_read_b128 v[234:237], v165 offset:49152
	ds_read_b128 v[238:241], v165 offset:50176
	ds_read_b128 v[242:245], v166 offset:49152
	ds_read_b128 v[246:249], v166 offset:50176
	s_barrier
	s_waitcnt lgkmcnt(0)
	s_setprio 1
	v_mfma_f32_16x16x32_bf16 v[8:11], v[176:179], v[0:3], v[60:63]
	v_mfma_f32_16x16x32_bf16 v[40:43], v[180:183], v[4:7], v[8:11]
	v_mfma_f32_16x16x32_bf16 v[8:11], v[176:179], v[202:205], v[56:59]
	v_mfma_f32_16x16x32_bf16 v[44:47], v[180:183], v[206:209], v[8:11]
	v_mfma_f32_16x16x32_bf16 v[8:11], v[184:187], v[0:3], v[52:55]
	v_mfma_f32_16x16x32_bf16 v[32:35], v[188:191], v[4:7], v[8:11]
	v_mfma_f32_16x16x32_bf16 v[8:11], v[184:187], v[202:205], v[48:51]
	v_mfma_f32_16x16x32_bf16 v[36:39], v[188:191], v[206:209], v[8:11]
	v_mfma_f32_16x16x32_bf16 v[8:11], v[234:237], v[0:3], v[226:229]
	v_mfma_f32_16x16x32_bf16 v[0:3], v[242:245], v[0:3], v[136:139]
	v_mfma_f32_16x16x32_bf16 v[8:11], v[238:241], v[4:7], v[8:11]
	v_mfma_f32_16x16x32_bf16 v[12:15], v[234:237], v[202:205], v[230:233]
	v_mfma_f32_16x16x32_bf16 v[0:3], v[246:249], v[4:7], v[0:3]
	v_mfma_f32_16x16x32_bf16 v[4:7], v[242:245], v[202:205], v[140:143]
	v_mfma_f32_16x16x32_bf16 v[12:15], v[238:241], v[206:209], v[12:15]
	v_mfma_f32_16x16x32_bf16 v[4:7], v[246:249], v[206:209], v[4:7]
	s_setprio 0
	s_setprio 1
	v_mfma_f32_16x16x32_bf16 v[16:19], v[184:187], v[214:217], v[16:19]
	v_mfma_f32_16x16x32_bf16 v[24:27], v[176:179], v[214:217], v[24:27]
	v_mfma_f32_16x16x32_bf16 v[52:55], v[188:191], v[218:221], v[16:19]
	v_mfma_f32_16x16x32_bf16 v[16:19], v[234:237], v[132:135], v[168:171]
	v_mfma_f32_16x16x32_bf16 v[28:31], v[176:179], v[132:135], v[28:31]
	v_mfma_f32_16x16x32_bf16 v[60:63], v[180:183], v[218:221], v[24:27]
	v_mfma_f32_16x16x32_bf16 v[20:23], v[184:187], v[132:135], v[20:23]
	v_mfma_f32_16x16x32_bf16 v[24:27], v[238:241], v[210:213], v[16:19]
	v_mfma_f32_16x16x32_bf16 v[16:19], v[234:237], v[214:217], v[172:175]
	v_mfma_f32_16x16x32_bf16 v[56:59], v[180:183], v[210:213], v[28:31]
	v_mfma_f32_16x16x32_bf16 v[48:51], v[188:191], v[210:213], v[20:23]
	v_mfma_f32_16x16x32_bf16 v[28:31], v[238:241], v[218:221], v[16:19]
	v_mfma_f32_16x16x32_bf16 v[16:19], v[242:245], v[132:135], v[194:197]
	v_mfma_f32_16x16x32_bf16 v[20:23], v[242:245], v[214:217], v[198:201]
	v_mfma_f32_16x16x32_bf16 v[16:19], v[246:249], v[210:213], v[16:19]
	v_mfma_f32_16x16x32_bf16 v[20:23], v[246:249], v[218:221], v[20:23]
	s_setprio 0
	s_andn2_b64 vcc, exec, s[40:41]
	s_barrier
	s_cbranch_vccnz .LBB0_286
	s_barrier

.LBB0_920:
	v_mov_b32_e32 v131, v133
	v_lshl_add_u64 v[0:1], s[24:25], 0, v[130:131]
	v_mov_b32_e32 v129, v133
	v_readfirstlane_b32 s21, v156
	v_lshl_add_u64 v[2:3], s[24:25], 0, v[128:129]
	v_lshl_add_u64 v[0:1], v[0:1], 0, s[8:9]
	s_mov_b32 m0, s21
	v_readfirstlane_b32 s21, v157
	v_lshl_add_u64 v[4:5], s[26:27], 0, v[130:131]
	s_waitcnt vmcnt(4)
	s_barrier
	global_load_lds_dwordx4 v[0:1], off
	v_lshl_add_u64 v[0:1], v[2:3], 0, s[8:9]
	s_mov_b32 m0, s21
	v_readfirstlane_b32 s21, v158
	v_lshl_add_u64 v[6:7], s[26:27], 0, v[128:129]
	global_load_lds_dwordx4 v[0:1], off
	v_lshl_add_u64 v[0:1], v[4:5], 0, s[8:9]
	s_mov_b32 m0, s21
	v_readfirstlane_b32 s21, v159
	v_lshl_add_u64 v[8:9], s[54:55], 0, v[130:131]
	global_load_lds_dwordx4 v[0:1], off
	v_lshl_add_u64 v[0:1], v[6:7], 0, s[8:9]
	s_mov_b32 m0, s21
	v_readfirstlane_b32 s21, v160
	v_lshl_add_u64 v[10:11], s[54:55], 0, v[128:129]
	global_load_lds_dwordx4 v[0:1], off
	v_lshl_add_u64 v[0:1], v[8:9], 0, s[8:9]
	s_mov_b32 m0, s21
	v_readfirstlane_b32 s21, v161
	global_load_lds_dwordx4 v[0:1], off
	v_lshl_add_u64 v[0:1], v[10:11], 0, s[8:9]
	s_mov_b32 m0, s21
	v_lshl_add_u64 v[136:137], s[56:57], 0, v[130:131]
	global_load_lds_dwordx4 v[0:1], off
	s_waitcnt vmcnt(6)
	v_mov_b32_e32 v0, 0
	v_lshl_add_u64 v[134:135], s[56:57], 0, v[128:129]
	v_lshl_add_u64 v[138:139], s[18:19], 0, v[130:131]
	v_lshl_add_u64 v[140:141], s[18:19], 0, v[128:129]
	v_lshl_add_u64 v[142:143], s[22:23], 0, v[130:131]
	v_lshl_add_u64 v[144:145], s[22:23], 0, v[128:129]
	s_mov_b32 s18, -2
	s_mov_b64 s[22:23], s[28:29]
	v_mov_b32_e32 v1, v0
	v_mov_b32_e32 v2, v0
	v_mov_b32_e32 v3, v0
	v_mov_b32_e32 v4, v0
	v_mov_b32_e32 v5, v0
	v_mov_b32_e32 v6, v0
	v_mov_b32_e32 v7, v0
	v_mov_b32_e32 v8, v0
	v_mov_b32_e32 v9, v0
	v_mov_b32_e32 v10, v0
	v_mov_b32_e32 v11, v0
	v_mov_b32_e32 v12, v0
	v_mov_b32_e32 v13, v0
	v_mov_b32_e32 v14, v0
	v_mov_b32_e32 v15, v0
	v_mov_b32_e32 v16, v0
	v_mov_b32_e32 v17, v0
	v_mov_b32_e32 v18, v0
	v_mov_b32_e32 v19, v0
	v_mov_b32_e32 v20, v0
	v_mov_b32_e32 v21, v0
	v_mov_b32_e32 v22, v0
	v_mov_b32_e32 v23, v0
	v_mov_b32_e32 v24, v0
	v_mov_b32_e32 v25, v0
	v_mov_b32_e32 v26, v0
	v_mov_b32_e32 v27, v0
	v_mov_b32_e32 v28, v0
	v_mov_b32_e32 v29, v0
	v_mov_b32_e32 v30, v0
	v_mov_b32_e32 v31, v0
	v_mov_b32_e32 v32, v0
	v_mov_b32_e32 v33, v0
	v_mov_b32_e32 v34, v0
	v_mov_b32_e32 v35, v0
	v_mov_b32_e32 v36, v0
	v_mov_b32_e32 v37, v0
	v_mov_b32_e32 v38, v0
	v_mov_b32_e32 v39, v0
	v_mov_b32_e32 v40, v0
	v_mov_b32_e32 v41, v0
	v_mov_b32_e32 v42, v0
	v_mov_b32_e32 v43, v0
	v_mov_b32_e32 v44, v0
	v_mov_b32_e32 v45, v0
	v_mov_b32_e32 v46, v0
	v_mov_b32_e32 v47, v0
	v_mov_b32_e32 v48, v0
	v_mov_b32_e32 v49, v0
	v_mov_b32_e32 v50, v0
	v_mov_b32_e32 v51, v0
	v_mov_b32_e32 v52, v0
	v_mov_b32_e32 v53, v0
	v_mov_b32_e32 v54, v0
	v_mov_b32_e32 v55, v0
	v_mov_b32_e32 v56, v0
	v_mov_b32_e32 v57, v0
	v_mov_b32_e32 v58, v0
	v_mov_b32_e32 v59, v0
	v_mov_b32_e32 v60, v0
	v_mov_b32_e32 v61, v0
	v_mov_b32_e32 v62, v0
	v_mov_b32_e32 v63, v0
	v_mov_b32_e32 v64, v0
	v_mov_b32_e32 v65, v0
	v_mov_b32_e32 v66, v0
	v_mov_b32_e32 v67, v0
	v_mov_b32_e32 v68, v0
	v_mov_b32_e32 v69, v0
	v_mov_b32_e32 v70, v0
	v_mov_b32_e32 v71, v0
	v_mov_b32_e32 v72, v0
	v_mov_b32_e32 v73, v0
	v_mov_b32_e32 v74, v0
	v_mov_b32_e32 v75, v0
	v_mov_b32_e32 v76, v0
	v_mov_b32_e32 v77, v0
	v_mov_b32_e32 v78, v0
	v_mov_b32_e32 v79, v0
	v_mov_b32_e32 v80, v0
	v_mov_b32_e32 v81, v0
	v_mov_b32_e32 v82, v0
	v_mov_b32_e32 v83, v0
	v_mov_b32_e32 v84, v0
	v_mov_b32_e32 v85, v0
	v_mov_b32_e32 v86, v0
	v_mov_b32_e32 v87, v0
	v_mov_b32_e32 v88, v0
	v_mov_b32_e32 v89, v0
	v_mov_b32_e32 v90, v0
	v_mov_b32_e32 v91, v0
	v_mov_b32_e32 v92, v0
	v_mov_b32_e32 v93, v0
	v_mov_b32_e32 v94, v0
	v_mov_b32_e32 v95, v0
	v_mov_b32_e32 v96, v0
	v_mov_b32_e32 v97, v0
	v_mov_b32_e32 v98, v0
	v_mov_b32_e32 v99, v0
	v_mov_b32_e32 v100, v0
	v_mov_b32_e32 v101, v0
	v_mov_b32_e32 v102, v0
	v_mov_b32_e32 v103, v0
	v_mov_b32_e32 v104, v0
	v_mov_b32_e32 v105, v0
	v_mov_b32_e32 v106, v0
	v_mov_b32_e32 v107, v0
	v_mov_b32_e32 v108, v0
	v_mov_b32_e32 v109, v0
	v_mov_b32_e32 v110, v0
	v_mov_b32_e32 v111, v0
	v_mov_b32_e32 v112, v0
	v_mov_b32_e32 v113, v0
	v_mov_b32_e32 v114, v0
	v_mov_b32_e32 v115, v0
	v_mov_b32_e32 v116, v0
	v_mov_b32_e32 v117, v0
	v_mov_b32_e32 v118, v0
	v_mov_b32_e32 v119, v0
	v_mov_b32_e32 v120, v0
	v_mov_b32_e32 v121, v0
	v_mov_b32_e32 v122, v0
	v_mov_b32_e32 v123, v0
	v_mov_b32_e32 v124, v0
	v_mov_b32_e32 v125, v0
	v_mov_b32_e32 v126, v0
	v_mov_b32_e32 v127, v0
.Lmy_rot_1:
	s_barrier
.LBB0_921:
	ds_read_b128 v[170:173], v162
	ds_read_b128 v[174:177], v162 offset:1024
	ds_read_b128 v[178:181], v162 offset:2048
	ds_read_b128 v[182:185], v162 offset:3072
	v_add_u32_e32 v167, 0xc000, v150
	v_lshl_add_u64 v[222:223], s[22:23], 0, v[142:143]
	v_readfirstlane_b32 s19, v167
	v_add_u32_e32 v129, s60, v147
	v_add_u32_e32 v131, s62, v147
	v_add_u32_e32 v132, s63, v147
	v_lshl_add_u64 v[168:169], v[222:223], 0, s[10:11]
	s_mov_b32 m0, s19
	ds_read_b128 v[186:189], v163
	ds_read_b128 v[190:193], v163 offset:1024
	ds_read_b128 v[194:197], v129
	ds_read_b128 v[198:201], v129 offset:1024
	ds_read_b128 v[202:205], v131
	ds_read_b128 v[206:209], v131 offset:1024
	ds_read_b128 v[210:213], v132
	ds_read_b128 v[214:217], v132 offset:1024
	global_load_lds_dwordx4 v[168:169], off
	v_add_u32_e32 v168, 0xe000, v150
	v_lshl_add_u64 v[238:239], s[22:23], 0, v[144:145]
	v_readfirstlane_b32 s19, v168
	v_lshl_add_u64 v[218:219], v[238:239], 0, s[10:11]
	s_mov_b32 m0, s19
	s_nop 0
	global_load_lds_dwordx4 v[218:219], off
	s_waitcnt lgkmcnt(8)
	s_barrier
	s_waitcnt lgkmcnt(0)
	s_setprio 1
	v_mfma_f32_16x16x32_bf16 v[124:127], v[186:189], v[170:173], v[124:127]
	v_mfma_f32_16x16x32_bf16 v[120:123], v[186:189], v[178:181], v[120:123]
	v_mfma_f32_16x16x32_bf16 v[116:119], v[194:197], v[170:173], v[116:119]
	v_mfma_f32_16x16x32_bf16 v[112:115], v[194:197], v[178:181], v[112:115]
	v_mfma_f32_16x16x32_bf16 v[108:111], v[202:205], v[170:173], v[108:111]
	v_mfma_f32_16x16x32_bf16 v[104:107], v[202:205], v[178:181], v[104:107]
	v_mfma_f32_16x16x32_bf16 v[100:103], v[210:213], v[170:173], v[100:103]
	v_mfma_f32_16x16x32_bf16 v[96:99], v[210:213], v[178:181], v[96:99]
	v_mfma_f32_16x16x32_bf16 v[124:127], v[190:193], v[174:177], v[124:127]
	v_mfma_f32_16x16x32_bf16 v[120:123], v[190:193], v[182:185], v[120:123]
	v_mfma_f32_16x16x32_bf16 v[116:119], v[198:201], v[174:177], v[116:119]
	v_mfma_f32_16x16x32_bf16 v[112:115], v[198:201], v[182:185], v[112:115]
	v_mfma_f32_16x16x32_bf16 v[108:111], v[206:209], v[174:177], v[108:111]
	v_mfma_f32_16x16x32_bf16 v[104:107], v[206:209], v[182:185], v[104:107]
	v_mfma_f32_16x16x32_bf16 v[100:103], v[214:217], v[174:177], v[100:103]
	v_mfma_f32_16x16x32_bf16 v[96:99], v[214:217], v[182:185], v[96:99]
	s_setprio 0
	s_barrier
	v_lshl_add_u64 v[240:241], s[22:23], 0, v[138:139]
	v_readfirstlane_b32 s19, v148
	v_lshl_add_u64 v[242:243], v[240:241], 0, s[12:13]
	s_mov_b32 m0, s19
	ds_read_b128 v[218:221], v164
	ds_read_b128 v[226:229], v164 offset:1024
	ds_read_b128 v[230:233], v164 offset:2048
	ds_read_b128 v[234:237], v164 offset:3072
	global_load_lds_dwordx4 v[242:243], off
	v_lshl_add_u64 v[242:243], s[22:23], 0, v[140:141]
	v_readfirstlane_b32 s19, v149
	v_lshl_add_u64 v[244:245], v[242:243], 0, s[12:13]
	s_mov_b32 m0, s19
	s_nop 0
	global_load_lds_dwordx4 v[244:245], off
	s_barrier
	s_waitcnt lgkmcnt(0)
	s_setprio 1
	v_mfma_f32_16x16x32_bf16 v[92:95], v[186:189], v[218:221], v[92:95]
	v_mfma_f32_16x16x32_bf16 v[88:91], v[186:189], v[230:233], v[88:91]
	v_mfma_f32_16x16x32_bf16 v[84:87], v[194:197], v[218:221], v[84:87]
	v_mfma_f32_16x16x32_bf16 v[80:83], v[194:197], v[230:233], v[80:83]
	v_mfma_f32_16x16x32_bf16 v[76:79], v[202:205], v[218:221], v[76:79]
	v_mfma_f32_16x16x32_bf16 v[72:75], v[202:205], v[230:233], v[72:75]
	v_mfma_f32_16x16x32_bf16 v[68:71], v[210:213], v[218:221], v[68:71]
	v_mfma_f32_16x16x32_bf16 v[64:67], v[210:213], v[230:233], v[64:67]
	v_mfma_f32_16x16x32_bf16 v[92:95], v[190:193], v[226:229], v[92:95]
	v_mfma_f32_16x16x32_bf16 v[88:91], v[190:193], v[234:237], v[88:91]
	v_mfma_f32_16x16x32_bf16 v[84:87], v[198:201], v[226:229], v[84:87]
	v_mfma_f32_16x16x32_bf16 v[80:83], v[198:201], v[234:237], v[80:83]
	v_mfma_f32_16x16x32_bf16 v[76:79], v[206:209], v[226:229], v[76:79]
	v_mfma_f32_16x16x32_bf16 v[72:75], v[206:209], v[234:237], v[72:75]
	v_mfma_f32_16x16x32_bf16 v[68:71], v[214:217], v[226:229], v[68:71]
	v_mfma_f32_16x16x32_bf16 v[64:67], v[214:217], v[234:237], v[64:67]
	s_setprio 0
	v_readfirstlane_b32 s19, v150
	v_lshl_add_u64 v[244:245], v[222:223], 0, s[14:15]
	s_mov_b32 m0, s19
	v_readfirstlane_b32 s19, v151
	s_barrier
	ds_read_b128 v[186:189], v163 offset:16384
	ds_read_b128 v[190:193], v163 offset:17408
	ds_read_b128 v[194:197], v129 offset:16384
	ds_read_b128 v[198:201], v129 offset:17408
	ds_read_b128 v[202:205], v131 offset:16384
	ds_read_b128 v[206:209], v131 offset:17408
	ds_read_b128 v[210:213], v132 offset:16384
	ds_read_b128 v[214:217], v132 offset:17408
	global_load_lds_dwordx4 v[244:245], off
	v_lshl_add_u64 v[244:245], v[238:239], 0, s[14:15]
	s_mov_b32 m0, s19
	s_nop 0
	global_load_lds_dwordx4 v[244:245], off
	s_barrier
	s_waitcnt lgkmcnt(0)
	s_setprio 1
	v_mfma_f32_16x16x32_bf16 v[60:63], v[186:189], v[170:173], v[60:63]
	v_mfma_f32_16x16x32_bf16 v[56:59], v[186:189], v[178:181], v[56:59]
	v_mfma_f32_16x16x32_bf16 v[52:55], v[194:197], v[170:173], v[52:55]
	v_mfma_f32_16x16x32_bf16 v[48:51], v[194:197], v[178:181], v[48:51]
	v_mfma_f32_16x16x32_bf16 v[44:47], v[202:205], v[170:173], v[44:47]
	v_mfma_f32_16x16x32_bf16 v[40:43], v[202:205], v[178:181], v[40:43]
	v_mfma_f32_16x16x32_bf16 v[36:39], v[210:213], v[170:173], v[36:39]
	v_mfma_f32_16x16x32_bf16 v[32:35], v[210:213], v[178:181], v[32:35]
	v_mfma_f32_16x16x32_bf16 v[60:63], v[190:193], v[174:177], v[60:63]
	v_mfma_f32_16x16x32_bf16 v[56:59], v[190:193], v[182:185], v[56:59]
	v_mfma_f32_16x16x32_bf16 v[52:55], v[198:201], v[174:177], v[52:55]
	v_mfma_f32_16x16x32_bf16 v[48:51], v[198:201], v[182:185], v[48:51]
	v_mfma_f32_16x16x32_bf16 v[44:47], v[206:209], v[174:177], v[44:47]
	v_mfma_f32_16x16x32_bf16 v[40:43], v[206:209], v[182:185], v[40:43]
	v_mfma_f32_16x16x32_bf16 v[36:39], v[214:217], v[174:177], v[36:39]
	v_mfma_f32_16x16x32_bf16 v[32:35], v[214:217], v[182:185], v[32:35]
	s_setprio 0
	s_barrier
	v_readfirstlane_b32 s19, v152
	v_lshl_add_u64 v[170:171], v[240:241], 0, s[16:17]
	s_mov_b32 m0, s19
	v_readfirstlane_b32 s19, v153
	global_load_lds_dwordx4 v[170:171], off
	v_lshl_add_u64 v[170:171], v[242:243], 0, s[16:17]
	s_mov_b32 m0, s19
	s_nop 0
	global_load_lds_dwordx4 v[170:171], off
	s_waitcnt vmcnt(6)
	s_barrier
	s_setprio 1
	v_mfma_f32_16x16x32_bf16 v[28:31], v[186:189], v[218:221], v[28:31]
	v_mfma_f32_16x16x32_bf16 v[24:27], v[186:189], v[230:233], v[24:27]
	v_mfma_f32_16x16x32_bf16 v[20:23], v[194:197], v[218:221], v[20:23]
	v_mfma_f32_16x16x32_bf16 v[16:19], v[194:197], v[230:233], v[16:19]
	v_mfma_f32_16x16x32_bf16 v[12:15], v[202:205], v[218:221], v[12:15]
	v_mfma_f32_16x16x32_bf16 v[8:11], v[202:205], v[230:233], v[8:11]
	v_mfma_f32_16x16x32_bf16 v[4:7], v[210:213], v[218:221], v[4:7]
	v_mfma_f32_16x16x32_bf16 v[0:3], v[210:213], v[230:233], v[0:3]
	v_mfma_f32_16x16x32_bf16 v[28:31], v[190:193], v[226:229], v[28:31]
	v_mfma_f32_16x16x32_bf16 v[24:27], v[190:193], v[234:237], v[24:27]
	v_mfma_f32_16x16x32_bf16 v[20:23], v[198:201], v[226:229], v[20:23]
	v_mfma_f32_16x16x32_bf16 v[16:19], v[198:201], v[234:237], v[16:19]
	v_mfma_f32_16x16x32_bf16 v[12:15], v[206:209], v[226:229], v[12:15]
	v_mfma_f32_16x16x32_bf16 v[8:11], v[206:209], v[234:237], v[8:11]
	v_mfma_f32_16x16x32_bf16 v[4:7], v[214:217], v[226:229], v[4:7]
	v_mfma_f32_16x16x32_bf16 v[0:3], v[214:217], v[234:237], v[0:3]
	s_setprio 0
	s_barrier
	ds_read_b128 v[170:173], v165
	ds_read_b128 v[174:177], v165 offset:1024
	ds_read_b128 v[178:181], v165 offset:2048
	ds_read_b128 v[182:185], v165 offset:3072
	v_readfirstlane_b32 s19, v154
	v_lshl_add_u64 v[218:219], v[222:223], 0, s[34:35]
	s_mov_b32 m0, s19
	v_readfirstlane_b32 s19, v155
	ds_read_b128 v[186:189], v163 offset:32768
	ds_read_b128 v[190:193], v163 offset:33792
	ds_read_b128 v[194:197], v129 offset:32768
	ds_read_b128 v[198:201], v129 offset:33792
	ds_read_b128 v[202:205], v131 offset:32768
	ds_read_b128 v[206:209], v131 offset:33792
	ds_read_b128 v[210:213], v132 offset:32768
	ds_read_b128 v[214:217], v132 offset:33792
	global_load_lds_dwordx4 v[218:219], off
	v_lshl_add_u64 v[218:219], v[238:239], 0, s[34:35]
	s_mov_b32 m0, s19
	s_nop 0
	global_load_lds_dwordx4 v[218:219], off
	s_waitcnt lgkmcnt(8)
	s_barrier
	s_waitcnt lgkmcnt(0)
	s_setprio 1
	v_mfma_f32_16x16x32_bf16 v[124:127], v[186:189], v[170:173], v[124:127]
	v_mfma_f32_16x16x32_bf16 v[120:123], v[186:189], v[178:181], v[120:123]
	v_mfma_f32_16x16x32_bf16 v[116:119], v[194:197], v[170:173], v[116:119]
	v_mfma_f32_16x16x32_bf16 v[112:115], v[194:197], v[178:181], v[112:115]
	v_mfma_f32_16x16x32_bf16 v[108:111], v[202:205], v[170:173], v[108:111]
	v_mfma_f32_16x16x32_bf16 v[104:107], v[202:205], v[178:181], v[104:107]
	v_mfma_f32_16x16x32_bf16 v[100:103], v[210:213], v[170:173], v[100:103]
	v_mfma_f32_16x16x32_bf16 v[96:99], v[210:213], v[178:181], v[96:99]
	v_mfma_f32_16x16x32_bf16 v[124:127], v[190:193], v[174:177], v[124:127]
	v_mfma_f32_16x16x32_bf16 v[120:123], v[190:193], v[182:185], v[120:123]
	v_mfma_f32_16x16x32_bf16 v[116:119], v[198:201], v[174:177], v[116:119]
	v_mfma_f32_16x16x32_bf16 v[112:115], v[198:201], v[182:185], v[112:115]
	v_mfma_f32_16x16x32_bf16 v[108:111], v[206:209], v[174:177], v[108:111]
	v_mfma_f32_16x16x32_bf16 v[104:107], v[206:209], v[182:185], v[104:107]
	v_mfma_f32_16x16x32_bf16 v[100:103], v[214:217], v[174:177], v[100:103]
	v_mfma_f32_16x16x32_bf16 v[96:99], v[214:217], v[182:185], v[96:99]
	s_setprio 0
	s_barrier
	v_readfirstlane_b32 s19, v156
	v_lshl_add_u64 v[244:245], v[240:241], 0, s[36:37]
	s_mov_b32 m0, s19
	v_readfirstlane_b32 s19, v157
	ds_read_b128 v[218:221], v166
	ds_read_b128 v[226:229], v166 offset:1024
	ds_read_b128 v[230:233], v166 offset:2048
	ds_read_b128 v[234:237], v166 offset:3072
	global_load_lds_dwordx4 v[244:245], off
	v_lshl_add_u64 v[244:245], v[242:243], 0, s[36:37]
	s_mov_b32 m0, s19
	s_nop 0
	global_load_lds_dwordx4 v[244:245], off
	s_barrier
	s_waitcnt lgkmcnt(0)
	s_setprio 1
	v_mfma_f32_16x16x32_bf16 v[92:95], v[186:189], v[218:221], v[92:95]
	v_mfma_f32_16x16x32_bf16 v[88:91], v[186:189], v[230:233], v[88:91]
	v_mfma_f32_16x16x32_bf16 v[84:87], v[194:197], v[218:221], v[84:87]
	v_mfma_f32_16x16x32_bf16 v[80:83], v[194:197], v[230:233], v[80:83]
	v_mfma_f32_16x16x32_bf16 v[76:79], v[202:205], v[218:221], v[76:79]
	v_mfma_f32_16x16x32_bf16 v[72:75], v[202:205], v[230:233], v[72:75]
	v_mfma_f32_16x16x32_bf16 v[68:71], v[210:213], v[218:221], v[68:71]
	v_mfma_f32_16x16x32_bf16 v[64:67], v[210:213], v[230:233], v[64:67]
	v_mfma_f32_16x16x32_bf16 v[92:95], v[190:193], v[226:229], v[92:95]
	v_mfma_f32_16x16x32_bf16 v[88:91], v[190:193], v[234:237], v[88:91]
	v_mfma_f32_16x16x32_bf16 v[84:87], v[198:201], v[226:229], v[84:87]
	v_mfma_f32_16x16x32_bf16 v[80:83], v[198:201], v[234:237], v[80:83]
	v_mfma_f32_16x16x32_bf16 v[76:79], v[206:209], v[226:229], v[76:79]
	v_mfma_f32_16x16x32_bf16 v[72:75], v[206:209], v[234:237], v[72:75]
	v_mfma_f32_16x16x32_bf16 v[68:71], v[214:217], v[226:229], v[68:71]
	v_mfma_f32_16x16x32_bf16 v[64:67], v[214:217], v[234:237], v[64:67]
	s_setprio 0
	v_readfirstlane_b32 s19, v158
	v_lshl_add_u64 v[222:223], v[222:223], 0, s[38:39]
	s_mov_b32 m0, s19
	v_readfirstlane_b32 s19, v159
	s_barrier
	ds_read_b128 v[186:189], v163 offset:49152
	ds_read_b128 v[190:193], v163 offset:50176
	ds_read_b128 v[194:197], v129 offset:49152
	ds_read_b128 v[198:201], v129 offset:50176
	ds_read_b128 v[202:205], v131 offset:49152
	ds_read_b128 v[206:209], v131 offset:50176
	ds_read_b128 v[210:213], v132 offset:49152
	ds_read_b128 v[214:217], v132 offset:50176
	global_load_lds_dwordx4 v[222:223], off
	v_lshl_add_u64 v[222:223], v[238:239], 0, s[38:39]
	s_mov_b32 m0, s19
	s_nop 0
	global_load_lds_dwordx4 v[222:223], off
	s_barrier
	s_waitcnt lgkmcnt(0)
	s_setprio 1
	v_mfma_f32_16x16x32_bf16 v[60:63], v[186:189], v[170:173], v[60:63]
	v_mfma_f32_16x16x32_bf16 v[56:59], v[186:189], v[178:181], v[56:59]
	v_mfma_f32_16x16x32_bf16 v[52:55], v[194:197], v[170:173], v[52:55]
	v_mfma_f32_16x16x32_bf16 v[48:51], v[194:197], v[178:181], v[48:51]
	v_mfma_f32_16x16x32_bf16 v[44:47], v[202:205], v[170:173], v[44:47]
	v_mfma_f32_16x16x32_bf16 v[40:43], v[202:205], v[178:181], v[40:43]
	v_mfma_f32_16x16x32_bf16 v[36:39], v[210:213], v[170:173], v[36:39]
	v_mfma_f32_16x16x32_bf16 v[32:35], v[210:213], v[178:181], v[32:35]
	v_mfma_f32_16x16x32_bf16 v[60:63], v[190:193], v[174:177], v[60:63]
	v_mfma_f32_16x16x32_bf16 v[56:59], v[190:193], v[182:185], v[56:59]
	v_mfma_f32_16x16x32_bf16 v[52:55], v[198:201], v[174:177], v[52:55]
	v_mfma_f32_16x16x32_bf16 v[48:51], v[198:201], v[182:185], v[48:51]
	v_mfma_f32_16x16x32_bf16 v[44:47], v[206:209], v[174:177], v[44:47]
	v_mfma_f32_16x16x32_bf16 v[40:43], v[206:209], v[182:185], v[40:43]
	v_mfma_f32_16x16x32_bf16 v[36:39], v[214:217], v[174:177], v[36:39]
	v_mfma_f32_16x16x32_bf16 v[32:35], v[214:217], v[182:185], v[32:35]
	s_setprio 0
	s_barrier
	v_readfirstlane_b32 s19, v160
	v_lshl_add_u64 v[170:171], v[240:241], 0, s[40:41]
	s_mov_b32 m0, s19
	v_readfirstlane_b32 s19, v161
	global_load_lds_dwordx4 v[170:171], off
	v_lshl_add_u64 v[170:171], v[242:243], 0, s[40:41]
	s_mov_b32 m0, s19
	s_nop 0
	global_load_lds_dwordx4 v[170:171], off
	s_waitcnt vmcnt(6)
	s_barrier
	s_setprio 1
	v_mfma_f32_16x16x32_bf16 v[28:31], v[186:189], v[218:221], v[28:31]
	v_mfma_f32_16x16x32_bf16 v[24:27], v[186:189], v[230:233], v[24:27]
	v_mfma_f32_16x16x32_bf16 v[20:23], v[194:197], v[218:221], v[20:23]
	v_mfma_f32_16x16x32_bf16 v[16:19], v[194:197], v[230:233], v[16:19]
	v_mfma_f32_16x16x32_bf16 v[12:15], v[202:205], v[218:221], v[12:15]
	v_mfma_f32_16x16x32_bf16 v[8:11], v[202:205], v[230:233], v[8:11]
	v_mfma_f32_16x16x32_bf16 v[4:7], v[210:213], v[218:221], v[4:7]
	v_mfma_f32_16x16x32_bf16 v[0:3], v[210:213], v[230:233], v[0:3]
	v_mfma_f32_16x16x32_bf16 v[28:31], v[190:193], v[226:229], v[28:31]
	v_mfma_f32_16x16x32_bf16 v[24:27], v[190:193], v[234:237], v[24:27]
	v_mfma_f32_16x16x32_bf16 v[20:23], v[198:201], v[226:229], v[20:23]
	v_mfma_f32_16x16x32_bf16 v[16:19], v[198:201], v[234:237], v[16:19]
	v_mfma_f32_16x16x32_bf16 v[12:15], v[206:209], v[226:229], v[12:15]
	v_mfma_f32_16x16x32_bf16 v[8:11], v[206:209], v[234:237], v[8:11]
	v_mfma_f32_16x16x32_bf16 v[4:7], v[214:217], v[226:229], v[4:7]
	v_mfma_f32_16x16x32_bf16 v[0:3], v[214:217], v[234:237], v[0:3]
	s_setprio 0
	s_add_i32 s18, s18, 2
	s_add_u32 s22, s22, 0x100
	s_addc_u32 s23, s23, 0
	s_cmp_lt_u32 s18, 28
	s_cbranch_scc1 .Lmy_rot_1
	s_barrier
	v_readfirstlane_b32 s18, v167
	v_lshl_add_u64 v[136:137], v[136:137], 0, s[44:45]
	s_mov_b32 m0, s18
	v_readfirstlane_b32 s18, v168
	ds_read_b128 v[138:141], v162
	ds_read_b128 v[142:145], v162 offset:1024
	ds_read_b128 v[170:173], v162 offset:2048
	ds_read_b128 v[174:177], v162 offset:3072
	ds_read_b128 v[178:181], v163
	ds_read_b128 v[182:185], v163 offset:1024
	ds_read_b128 v[186:189], v129
	ds_read_b128 v[190:193], v129 offset:1024
	ds_read_b128 v[194:197], v131
	ds_read_b128 v[198:201], v131 offset:1024
	ds_read_b128 v[202:205], v132
	ds_read_b128 v[206:209], v132 offset:1024
	global_load_lds_dwordx4 v[136:137], off
	v_lshl_add_u64 v[134:135], v[134:135], 0, s[44:45]
	s_mov_b32 m0, s18
	s_nop 0
	global_load_lds_dwordx4 v[134:135], off
	s_barrier
	s_waitcnt lgkmcnt(0)
	s_setprio 1
	v_mfma_f32_16x16x32_bf16 v[124:127], v[178:181], v[138:141], v[124:127]
	v_mfma_f32_16x16x32_bf16 v[120:123], v[178:181], v[170:173], v[120:123]
	v_mfma_f32_16x16x32_bf16 v[116:119], v[186:189], v[138:141], v[116:119]
	v_mfma_f32_16x16x32_bf16 v[112:115], v[186:189], v[170:173], v[112:115]
	v_mfma_f32_16x16x32_bf16 v[124:127], v[182:185], v[142:145], v[124:127]
	v_mfma_f32_16x16x32_bf16 v[120:123], v[182:185], v[174:177], v[120:123]
	v_mfma_f32_16x16x32_bf16 v[116:119], v[190:193], v[142:145], v[116:119]
	v_mfma_f32_16x16x32_bf16 v[112:115], v[190:193], v[174:177], v[112:115]
	v_mfma_f32_16x16x32_bf16 v[108:111], v[194:197], v[138:141], v[108:111]
	v_mfma_f32_16x16x32_bf16 v[104:107], v[194:197], v[170:173], v[104:107]
	v_mfma_f32_16x16x32_bf16 v[100:103], v[202:205], v[138:141], v[100:103]
	v_mfma_f32_16x16x32_bf16 v[96:99], v[202:205], v[170:173], v[96:99]
	v_mfma_f32_16x16x32_bf16 v[134:137], v[198:201], v[142:145], v[108:111]
	v_mfma_f32_16x16x32_bf16 v[210:213], v[198:201], v[174:177], v[104:107]
	v_mfma_f32_16x16x32_bf16 v[214:217], v[206:209], v[142:145], v[100:103]
	v_mfma_f32_16x16x32_bf16 v[218:221], v[206:209], v[174:177], v[96:99]
	s_setprio 0
	s_barrier
	s_nop 1
	ds_read_b128 v[96:99], v164
	ds_read_b128 v[100:103], v164 offset:1024
	ds_read_b128 v[104:107], v164 offset:2048
	ds_read_b128 v[108:111], v164 offset:3072
	s_barrier
	s_waitcnt lgkmcnt(0)
	s_setprio 1
	v_mfma_f32_16x16x32_bf16 v[92:95], v[178:181], v[96:99], v[92:95]
	v_mfma_f32_16x16x32_bf16 v[88:91], v[178:181], v[104:107], v[88:91]
	v_mfma_f32_16x16x32_bf16 v[84:87], v[186:189], v[96:99], v[84:87]
	v_mfma_f32_16x16x32_bf16 v[80:83], v[186:189], v[104:107], v[80:83]
	v_mfma_f32_16x16x32_bf16 v[92:95], v[182:185], v[100:103], v[92:95]
	v_mfma_f32_16x16x32_bf16 v[88:91], v[182:185], v[108:111], v[88:91]
	v_mfma_f32_16x16x32_bf16 v[84:87], v[190:193], v[100:103], v[84:87]
	v_mfma_f32_16x16x32_bf16 v[80:83], v[190:193], v[108:111], v[80:83]
	v_mfma_f32_16x16x32_bf16 v[76:79], v[194:197], v[96:99], v[76:79]
	v_mfma_f32_16x16x32_bf16 v[72:75], v[194:197], v[104:107], v[72:75]
	v_mfma_f32_16x16x32_bf16 v[68:71], v[202:205], v[96:99], v[68:71]
	v_mfma_f32_16x16x32_bf16 v[64:67], v[202:205], v[104:107], v[64:67]
	v_mfma_f32_16x16x32_bf16 v[178:181], v[198:201], v[100:103], v[76:79]
	v_mfma_f32_16x16x32_bf16 v[182:185], v[198:201], v[108:111], v[72:75]
	v_mfma_f32_16x16x32_bf16 v[186:189], v[206:209], v[100:103], v[68:71]
	v_mfma_f32_16x16x32_bf16 v[190:193], v[206:209], v[108:111], v[64:67]
	s_setprio 0
	s_barrier
	s_nop 1
	ds_read_b128 v[64:67], v163 offset:16384
	ds_read_b128 v[68:71], v163 offset:17408
	ds_read_b128 v[72:75], v129 offset:16384
	ds_read_b128 v[76:79], v129 offset:17408
	ds_read_b128 v[194:197], v131 offset:16384
	ds_read_b128 v[198:201], v131 offset:17408
	ds_read_b128 v[202:205], v132 offset:16384
	ds_read_b128 v[206:209], v132 offset:17408
	s_waitcnt vmcnt(4)
	s_barrier
	s_waitcnt lgkmcnt(0)
	s_setprio 1
	v_mfma_f32_16x16x32_bf16 v[60:63], v[64:67], v[138:141], v[60:63]
	v_mfma_f32_16x16x32_bf16 v[56:59], v[64:67], v[170:173], v[56:59]
	v_mfma_f32_16x16x32_bf16 v[52:55], v[72:75], v[138:141], v[52:55]
	v_mfma_f32_16x16x32_bf16 v[48:51], v[72:75], v[170:173], v[48:51]
	v_mfma_f32_16x16x32_bf16 v[60:63], v[68:71], v[142:145], v[60:63]
	v_mfma_f32_16x16x32_bf16 v[56:59], v[68:71], v[174:177], v[56:59]
	v_mfma_f32_16x16x32_bf16 v[52:55], v[76:79], v[142:145], v[52:55]
	v_mfma_f32_16x16x32_bf16 v[48:51], v[76:79], v[174:177], v[48:51]
	v_mfma_f32_16x16x32_bf16 v[44:47], v[194:197], v[138:141], v[44:47]
	v_mfma_f32_16x16x32_bf16 v[40:43], v[194:197], v[170:173], v[40:43]
	v_mfma_f32_16x16x32_bf16 v[36:39], v[202:205], v[138:141], v[36:39]
	v_mfma_f32_16x16x32_bf16 v[32:35], v[202:205], v[170:173], v[32:35]
	v_mfma_f32_16x16x32_bf16 v[226:229], v[198:201], v[142:145], v[44:47]
	v_mfma_f32_16x16x32_bf16 v[230:233], v[198:201], v[174:177], v[40:43]
	v_mfma_f32_16x16x32_bf16 v[138:141], v[206:209], v[142:145], v[36:39]
	v_mfma_f32_16x16x32_bf16 v[142:145], v[206:209], v[174:177], v[32:35]
	s_setprio 0
	s_setprio 1
	v_mfma_f32_16x16x32_bf16 v[28:31], v[64:67], v[96:99], v[28:31]
	v_mfma_f32_16x16x32_bf16 v[24:27], v[64:67], v[104:107], v[24:27]
	v_mfma_f32_16x16x32_bf16 v[20:23], v[72:75], v[96:99], v[20:23]
	v_mfma_f32_16x16x32_bf16 v[16:19], v[72:75], v[104:107], v[16:19]
	v_mfma_f32_16x16x32_bf16 v[28:31], v[68:71], v[100:103], v[28:31]
	v_mfma_f32_16x16x32_bf16 v[24:27], v[68:71], v[108:111], v[24:27]
	v_mfma_f32_16x16x32_bf16 v[20:23], v[76:79], v[100:103], v[20:23]
	v_mfma_f32_16x16x32_bf16 v[16:19], v[76:79], v[108:111], v[16:19]
	v_mfma_f32_16x16x32_bf16 v[12:15], v[194:197], v[96:99], v[12:15]
	v_mfma_f32_16x16x32_bf16 v[8:11], v[194:197], v[104:107], v[8:11]
	v_mfma_f32_16x16x32_bf16 v[4:7], v[202:205], v[96:99], v[4:7]
	v_mfma_f32_16x16x32_bf16 v[0:3], v[202:205], v[104:107], v[0:3]
	v_mfma_f32_16x16x32_bf16 v[168:171], v[198:201], v[100:103], v[12:15]
	v_mfma_f32_16x16x32_bf16 v[172:175], v[198:201], v[108:111], v[8:11]
	v_mfma_f32_16x16x32_bf16 v[194:197], v[206:209], v[100:103], v[4:7]
	v_mfma_f32_16x16x32_bf16 v[198:201], v[206:209], v[108:111], v[0:3]
	s_setprio 0
	s_barrier
	s_nop 1
	ds_read_b128 v[0:3], v165
	ds_read_b128 v[4:7], v165 offset:1024
	ds_read_b128 v[202:205], v165 offset:2048
	ds_read_b128 v[206:209], v165 offset:3072
	ds_read_b128 v[8:11], v163 offset:32768
	ds_read_b128 v[12:15], v163 offset:33792
	ds_read_b128 v[32:35], v129 offset:32768
	ds_read_b128 v[36:39], v129 offset:33792
	ds_read_b128 v[40:43], v131 offset:32768
	ds_read_b128 v[44:47], v131 offset:33792
	ds_read_b128 v[234:237], v132 offset:32768
	ds_read_b128 v[238:241], v132 offset:33792
	s_waitcnt vmcnt(2)
	s_barrier
	s_waitcnt lgkmcnt(0)
	s_setprio 1
	v_mfma_f32_16x16x32_bf16 v[64:67], v[8:11], v[0:3], v[124:127]
	v_mfma_f32_16x16x32_bf16 v[104:107], v[12:15], v[4:7], v[64:67]
	v_mfma_f32_16x16x32_bf16 v[64:67], v[8:11], v[202:205], v[120:123]
	v_mfma_f32_16x16x32_bf16 v[108:111], v[12:15], v[206:209], v[64:67]
	v_mfma_f32_16x16x32_bf16 v[64:67], v[32:35], v[0:3], v[116:119]
	v_mfma_f32_16x16x32_bf16 v[96:99], v[36:39], v[4:7], v[64:67]
	v_mfma_f32_16x16x32_bf16 v[64:67], v[32:35], v[202:205], v[112:115]
	v_mfma_f32_16x16x32_bf16 v[100:103], v[36:39], v[206:209], v[64:67]
	v_mfma_f32_16x16x32_bf16 v[64:67], v[40:43], v[0:3], v[134:137]
	v_mfma_f32_16x16x32_bf16 v[72:75], v[44:47], v[4:7], v[64:67]
	v_mfma_f32_16x16x32_bf16 v[64:67], v[40:43], v[202:205], v[210:213]
	v_mfma_f32_16x16x32_bf16 v[76:79], v[44:47], v[206:209], v[64:67]
	v_mfma_f32_16x16x32_bf16 v[64:67], v[234:237], v[0:3], v[214:217]
	v_mfma_f32_16x16x32_bf16 v[68:71], v[234:237], v[202:205], v[218:221]
	v_mfma_f32_16x16x32_bf16 v[64:67], v[238:241], v[4:7], v[64:67]
	v_mfma_f32_16x16x32_bf16 v[68:71], v[238:241], v[206:209], v[68:71]
	s_setprio 0
	s_barrier
	ds_read_b128 v[134:137], v166
	ds_read_b128 v[210:213], v166 offset:1024
	ds_read_b128 v[214:217], v166 offset:2048
	ds_read_b128 v[218:221], v166 offset:3072
	s_waitcnt vmcnt(0)
	s_barrier
	s_waitcnt lgkmcnt(0)
	s_setprio 1
	v_mfma_f32_16x16x32_bf16 v[92:95], v[8:11], v[134:137], v[92:95]
	v_mfma_f32_16x16x32_bf16 v[8:11], v[8:11], v[214:217], v[88:91]
	v_mfma_f32_16x16x32_bf16 v[124:127], v[12:15], v[218:221], v[8:11]
	v_mfma_f32_16x16x32_bf16 v[8:11], v[32:35], v[134:137], v[84:87]
	v_mfma_f32_16x16x32_bf16 v[112:115], v[36:39], v[210:213], v[8:11]
	v_mfma_f32_16x16x32_bf16 v[8:11], v[32:35], v[214:217], v[80:83]
	v_mfma_f32_16x16x32_bf16 v[116:119], v[36:39], v[218:221], v[8:11]
	v_mfma_f32_16x16x32_bf16 v[8:11], v[40:43], v[134:137], v[178:181]
	v_mfma_f32_16x16x32_bf16 v[88:91], v[44:47], v[210:213], v[8:11]
	v_mfma_f32_16x16x32_bf16 v[8:11], v[40:43], v[214:217], v[182:185]
	v_mfma_f32_16x16x32_bf16 v[120:123], v[12:15], v[210:213], v[92:95]
	v_mfma_f32_16x16x32_bf16 v[92:95], v[44:47], v[218:221], v[8:11]
	v_mfma_f32_16x16x32_bf16 v[8:11], v[234:237], v[134:137], v[186:189]
	v_mfma_f32_16x16x32_bf16 v[80:83], v[238:241], v[210:213], v[8:11]
	v_mfma_f32_16x16x32_bf16 v[8:11], v[234:237], v[214:217], v[190:193]
	v_mfma_f32_16x16x32_bf16 v[84:87], v[238:241], v[218:221], v[8:11]
	s_setprio 0
	s_barrier
	ds_read_b128 v[176:179], v163 offset:49152
	ds_read_b128 v[180:183], v163 offset:50176
	ds_read_b128 v[184:187], v129 offset:49152
	ds_read_b128 v[188:191], v129 offset:50176
	ds_read_b128 v[234:237], v131 offset:49152
	ds_read_b128 v[238:241], v131 offset:50176
	ds_read_b128 v[242:245], v132 offset:49152
	ds_read_b128 v[246:249], v132 offset:50176
	s_barrier
	s_waitcnt lgkmcnt(0)
	s_setprio 1
	v_mfma_f32_16x16x32_bf16 v[8:11], v[176:179], v[0:3], v[60:63]
	v_mfma_f32_16x16x32_bf16 v[40:43], v[180:183], v[4:7], v[8:11]
	v_mfma_f32_16x16x32_bf16 v[8:11], v[176:179], v[202:205], v[56:59]
	v_mfma_f32_16x16x32_bf16 v[44:47], v[180:183], v[206:209], v[8:11]
	v_mfma_f32_16x16x32_bf16 v[8:11], v[184:187], v[0:3], v[52:55]
	v_mfma_f32_16x16x32_bf16 v[32:35], v[188:191], v[4:7], v[8:11]
	v_mfma_f32_16x16x32_bf16 v[8:11], v[184:187], v[202:205], v[48:51]
	v_mfma_f32_16x16x32_bf16 v[36:39], v[188:191], v[206:209], v[8:11]
	v_mfma_f32_16x16x32_bf16 v[8:11], v[234:237], v[0:3], v[226:229]
	v_mfma_f32_16x16x32_bf16 v[0:3], v[242:245], v[0:3], v[138:141]
	v_mfma_f32_16x16x32_bf16 v[8:11], v[238:241], v[4:7], v[8:11]
	v_mfma_f32_16x16x32_bf16 v[12:15], v[234:237], v[202:205], v[230:233]
	v_mfma_f32_16x16x32_bf16 v[0:3], v[246:249], v[4:7], v[0:3]
	v_mfma_f32_16x16x32_bf16 v[4:7], v[242:245], v[202:205], v[142:145]
	v_mfma_f32_16x16x32_bf16 v[12:15], v[238:241], v[206:209], v[12:15]
	v_mfma_f32_16x16x32_bf16 v[4:7], v[246:249], v[206:209], v[4:7]
	s_setprio 0
	s_setprio 1
	v_mfma_f32_16x16x32_bf16 v[16:19], v[184:187], v[214:217], v[16:19]
	v_mfma_f32_16x16x32_bf16 v[24:27], v[176:179], v[214:217], v[24:27]
	v_mfma_f32_16x16x32_bf16 v[52:55], v[188:191], v[218:221], v[16:19]
	v_mfma_f32_16x16x32_bf16 v[16:19], v[234:237], v[134:137], v[168:171]
	v_mfma_f32_16x16x32_bf16 v[28:31], v[176:179], v[134:137], v[28:31]
	v_mfma_f32_16x16x32_bf16 v[60:63], v[180:183], v[218:221], v[24:27]
	v_mfma_f32_16x16x32_bf16 v[20:23], v[184:187], v[134:137], v[20:23]
	v_mfma_f32_16x16x32_bf16 v[24:27], v[238:241], v[210:213], v[16:19]
	v_mfma_f32_16x16x32_bf16 v[16:19], v[234:237], v[214:217], v[172:175]
	v_mfma_f32_16x16x32_bf16 v[56:59], v[180:183], v[210:213], v[28:31]
	v_mfma_f32_16x16x32_bf16 v[48:51], v[188:191], v[210:213], v[20:23]
	v_mfma_f32_16x16x32_bf16 v[28:31], v[238:241], v[218:221], v[16:19]
	v_mfma_f32_16x16x32_bf16 v[16:19], v[242:245], v[134:137], v[194:197]
	v_mfma_f32_16x16x32_bf16 v[20:23], v[242:245], v[214:217], v[198:201]
	v_mfma_f32_16x16x32_bf16 v[16:19], v[246:249], v[210:213], v[16:19]
	v_mfma_f32_16x16x32_bf16 v[20:23], v[246:249], v[218:221], v[20:23]
	s_setprio 0
	s_andn2_b64 vcc, exec, s[4:5]
	s_barrier
	s_cbranch_vccnz .LBB0_913
	s_barrier
	s_branch .LBB0_913

.LBB0_1470:
	v_mov_b32_e32 v129, v131
	v_lshl_add_u64 v[0:1], s[42:43], 0, v[130:131]
	v_lshl_add_u64 v[4:5], s[44:45], 0, v[130:131]
	v_lshl_add_u64 v[6:7], s[44:45], 0, v[128:129]
	v_readfirstlane_b32 s44, v155
	v_lshl_add_u64 v[2:3], s[42:43], 0, v[128:129]
	v_lshl_add_u64 v[0:1], v[0:1], 0, s[8:9]
	s_mov_b32 m0, s44
	v_readfirstlane_b32 s44, v156
	s_waitcnt vmcnt(4)
	s_barrier
	global_load_lds_dwordx4 v[0:1], off
	v_lshl_add_u64 v[0:1], v[2:3], 0, s[8:9]
	s_mov_b32 m0, s44
	v_readfirstlane_b32 s44, v150
	global_load_lds_dwordx4 v[0:1], off
	v_lshl_add_u64 v[0:1], v[4:5], 0, s[8:9]
	s_mov_b32 m0, s44
	v_readfirstlane_b32 s44, v151
	s_add_u32 s42, s42, 0x160080
	global_load_lds_dwordx4 v[0:1], off
	v_lshl_add_u64 v[0:1], v[6:7], 0, s[8:9]
	s_mov_b32 m0, s44
	s_addc_u32 s43, s43, 0
	v_readfirstlane_b32 s44, v157
	global_load_lds_dwordx4 v[0:1], off
	v_lshl_add_u64 v[0:1], s[42:43], 0, v[130:131]
	s_mov_b32 m0, s44
	v_lshl_add_u64 v[132:133], s[18:19], 0, v[130:131]
	global_load_lds_dwordx4 v[0:1], off
	v_lshl_add_u64 v[0:1], s[42:43], 0, v[128:129]
	v_readfirstlane_b32 s42, v158
	s_mov_b32 m0, s42
	v_lshl_add_u64 v[134:135], s[18:19], 0, v[128:129]
	global_load_lds_dwordx4 v[0:1], off
	s_waitcnt vmcnt(6)
	v_mov_b32_e32 v0, 0
	v_lshl_add_u64 v[136:137], s[26:27], 0, v[130:131]
	v_lshl_add_u64 v[138:139], s[26:27], 0, v[128:129]
	s_mov_b32 s18, -2
	s_mov_b64 s[26:27], s[28:29]
	v_mov_b32_e32 v1, v0
	v_mov_b32_e32 v2, v0
	v_mov_b32_e32 v3, v0
	v_mov_b32_e32 v4, v0
	v_mov_b32_e32 v5, v0
	v_mov_b32_e32 v6, v0
	v_mov_b32_e32 v7, v0
	v_mov_b32_e32 v8, v0
	v_mov_b32_e32 v9, v0
	v_mov_b32_e32 v10, v0
	v_mov_b32_e32 v11, v0
	v_mov_b32_e32 v12, v0
	v_mov_b32_e32 v13, v0
	v_mov_b32_e32 v14, v0
	v_mov_b32_e32 v15, v0
	v_mov_b32_e32 v16, v0
	v_mov_b32_e32 v17, v0
	v_mov_b32_e32 v18, v0
	v_mov_b32_e32 v19, v0
	v_mov_b32_e32 v20, v0
	v_mov_b32_e32 v21, v0
	v_mov_b32_e32 v22, v0
	v_mov_b32_e32 v23, v0
	v_mov_b32_e32 v24, v0
	v_mov_b32_e32 v25, v0
	v_mov_b32_e32 v26, v0
	v_mov_b32_e32 v27, v0
	v_mov_b32_e32 v28, v0
	v_mov_b32_e32 v29, v0
	v_mov_b32_e32 v30, v0
	v_mov_b32_e32 v31, v0
	v_mov_b32_e32 v32, v0
	v_mov_b32_e32 v33, v0
	v_mov_b32_e32 v34, v0
	v_mov_b32_e32 v35, v0
	v_mov_b32_e32 v36, v0
	v_mov_b32_e32 v37, v0
	v_mov_b32_e32 v38, v0
	v_mov_b32_e32 v39, v0
	v_mov_b32_e32 v40, v0
	v_mov_b32_e32 v41, v0
	v_mov_b32_e32 v42, v0
	v_mov_b32_e32 v43, v0
	v_mov_b32_e32 v44, v0
	v_mov_b32_e32 v45, v0
	v_mov_b32_e32 v46, v0
	v_mov_b32_e32 v47, v0
	v_mov_b32_e32 v48, v0
	v_mov_b32_e32 v49, v0
	v_mov_b32_e32 v50, v0
	v_mov_b32_e32 v51, v0
	v_mov_b32_e32 v52, v0
	v_mov_b32_e32 v53, v0
	v_mov_b32_e32 v54, v0
	v_mov_b32_e32 v55, v0
	v_mov_b32_e32 v56, v0
	v_mov_b32_e32 v57, v0
	v_mov_b32_e32 v58, v0
	v_mov_b32_e32 v59, v0
	v_mov_b32_e32 v60, v0
	v_mov_b32_e32 v61, v0
	v_mov_b32_e32 v62, v0
	v_mov_b32_e32 v63, v0
	v_mov_b32_e32 v64, v0
	v_mov_b32_e32 v65, v0
	v_mov_b32_e32 v66, v0
	v_mov_b32_e32 v67, v0
	v_mov_b32_e32 v68, v0
	v_mov_b32_e32 v69, v0
	v_mov_b32_e32 v70, v0
	v_mov_b32_e32 v71, v0
	v_mov_b32_e32 v72, v0
	v_mov_b32_e32 v73, v0
	v_mov_b32_e32 v74, v0
	v_mov_b32_e32 v75, v0
	v_mov_b32_e32 v76, v0
	v_mov_b32_e32 v77, v0
	v_mov_b32_e32 v78, v0
	v_mov_b32_e32 v79, v0
	v_mov_b32_e32 v80, v0
	v_mov_b32_e32 v81, v0
	v_mov_b32_e32 v82, v0
	v_mov_b32_e32 v83, v0
	v_mov_b32_e32 v84, v0
	v_mov_b32_e32 v85, v0
	v_mov_b32_e32 v86, v0
	v_mov_b32_e32 v87, v0
	v_mov_b32_e32 v88, v0
	v_mov_b32_e32 v89, v0
	v_mov_b32_e32 v90, v0
	v_mov_b32_e32 v91, v0
	v_mov_b32_e32 v92, v0
	v_mov_b32_e32 v93, v0
	v_mov_b32_e32 v94, v0
	v_mov_b32_e32 v95, v0
	v_mov_b32_e32 v96, v0
	v_mov_b32_e32 v97, v0
	v_mov_b32_e32 v98, v0
	v_mov_b32_e32 v99, v0
	v_mov_b32_e32 v100, v0
	v_mov_b32_e32 v101, v0
	v_mov_b32_e32 v102, v0
	v_mov_b32_e32 v103, v0
	v_mov_b32_e32 v104, v0
	v_mov_b32_e32 v105, v0
	v_mov_b32_e32 v106, v0
	v_mov_b32_e32 v107, v0
	v_mov_b32_e32 v108, v0
	v_mov_b32_e32 v109, v0
	v_mov_b32_e32 v110, v0
	v_mov_b32_e32 v111, v0
	v_mov_b32_e32 v112, v0
	v_mov_b32_e32 v113, v0
	v_mov_b32_e32 v114, v0
	v_mov_b32_e32 v115, v0
	v_mov_b32_e32 v116, v0
	v_mov_b32_e32 v117, v0
	v_mov_b32_e32 v118, v0
	v_mov_b32_e32 v119, v0
	v_mov_b32_e32 v120, v0
	v_mov_b32_e32 v121, v0
	v_mov_b32_e32 v122, v0
	v_mov_b32_e32 v123, v0
	v_mov_b32_e32 v124, v0
	v_mov_b32_e32 v125, v0
	v_mov_b32_e32 v126, v0
	v_mov_b32_e32 v127, v0
.Lmy_rot_2:
	s_barrier
.LBB0_1471:
	ds_read_b128 v[166:169], v152
	ds_read_b128 v[170:173], v152 offset:1024
	ds_read_b128 v[174:177], v152 offset:2048
	ds_read_b128 v[178:181], v152 offset:3072
	v_add_u32_e32 v164, 0xc000, v144
	v_lshl_add_u64 v[222:223], s[26:27], 0, v[136:137]
	v_readfirstlane_b32 s19, v164
	v_add_u32_e32 v165, 0xe000, v144
	v_add_u32_e32 v162, s48, v141
	v_add_u32_e32 v163, s49, v141
	v_lshl_add_u64 v[214:215], v[222:223], 0, s[10:11]
	s_mov_b32 m0, s19
	v_lshl_add_u64 v[234:235], s[26:27], 0, v[138:139]
	v_readfirstlane_b32 s19, v165
	ds_read_b128 v[182:185], v153
	ds_read_b128 v[186:189], v153 offset:1024
	ds_read_b128 v[190:193], v154
	ds_read_b128 v[194:197], v154 offset:1024
	ds_read_b128 v[198:201], v162
	ds_read_b128 v[202:205], v162 offset:1024
	ds_read_b128 v[206:209], v163
	ds_read_b128 v[210:213], v163 offset:1024
	global_load_lds_dwordx4 v[214:215], off
	v_lshl_add_u64 v[214:215], v[234:235], 0, s[10:11]
	s_mov_b32 m0, s19
	s_nop 0
	global_load_lds_dwordx4 v[214:215], off
	s_waitcnt lgkmcnt(8)
	s_barrier
	s_waitcnt lgkmcnt(0)
	s_setprio 1
	v_mfma_f32_16x16x32_bf16 v[124:127], v[182:185], v[166:169], v[124:127]
	v_mfma_f32_16x16x32_bf16 v[120:123], v[182:185], v[174:177], v[120:123]
	v_mfma_f32_16x16x32_bf16 v[116:119], v[190:193], v[166:169], v[116:119]
	v_mfma_f32_16x16x32_bf16 v[112:115], v[190:193], v[174:177], v[112:115]
	v_mfma_f32_16x16x32_bf16 v[108:111], v[198:201], v[166:169], v[108:111]
	v_mfma_f32_16x16x32_bf16 v[104:107], v[198:201], v[174:177], v[104:107]
	v_mfma_f32_16x16x32_bf16 v[100:103], v[206:209], v[166:169], v[100:103]
	v_mfma_f32_16x16x32_bf16 v[96:99], v[206:209], v[174:177], v[96:99]
	v_mfma_f32_16x16x32_bf16 v[124:127], v[186:189], v[170:173], v[124:127]
	v_mfma_f32_16x16x32_bf16 v[120:123], v[186:189], v[178:181], v[120:123]
	v_mfma_f32_16x16x32_bf16 v[116:119], v[194:197], v[170:173], v[116:119]
	v_mfma_f32_16x16x32_bf16 v[112:115], v[194:197], v[178:181], v[112:115]
	v_mfma_f32_16x16x32_bf16 v[108:111], v[202:205], v[170:173], v[108:111]
	v_mfma_f32_16x16x32_bf16 v[104:107], v[202:205], v[178:181], v[104:107]
	v_mfma_f32_16x16x32_bf16 v[100:103], v[210:213], v[170:173], v[100:103]
	v_mfma_f32_16x16x32_bf16 v[96:99], v[210:213], v[178:181], v[96:99]
	s_setprio 0
	s_barrier
	v_lshl_add_u64 v[236:237], s[26:27], 0, v[132:133]
	v_readfirstlane_b32 s19, v142
	v_lshl_add_u64 v[238:239], v[236:237], 0, s[12:13]
	s_mov_b32 m0, s19
	ds_read_b128 v[214:217], v159
	ds_read_b128 v[218:221], v159 offset:1024
	ds_read_b128 v[226:229], v159 offset:2048
	ds_read_b128 v[230:233], v159 offset:3072
	global_load_lds_dwordx4 v[238:239], off
	v_lshl_add_u64 v[238:239], s[26:27], 0, v[134:135]
	v_readfirstlane_b32 s19, v143
	v_lshl_add_u64 v[240:241], v[238:239], 0, s[12:13]
	s_mov_b32 m0, s19
	s_nop 0
	global_load_lds_dwordx4 v[240:241], off
	s_barrier
	s_waitcnt lgkmcnt(0)
	s_setprio 1
	v_mfma_f32_16x16x32_bf16 v[92:95], v[182:185], v[214:217], v[92:95]
	v_mfma_f32_16x16x32_bf16 v[88:91], v[182:185], v[226:229], v[88:91]
	v_mfma_f32_16x16x32_bf16 v[84:87], v[190:193], v[214:217], v[84:87]
	v_mfma_f32_16x16x32_bf16 v[80:83], v[190:193], v[226:229], v[80:83]
	v_mfma_f32_16x16x32_bf16 v[76:79], v[198:201], v[214:217], v[76:79]
	v_mfma_f32_16x16x32_bf16 v[72:75], v[198:201], v[226:229], v[72:75]
	v_mfma_f32_16x16x32_bf16 v[68:71], v[206:209], v[214:217], v[68:71]
	v_mfma_f32_16x16x32_bf16 v[64:67], v[206:209], v[226:229], v[64:67]
	v_mfma_f32_16x16x32_bf16 v[92:95], v[186:189], v[218:221], v[92:95]
	v_mfma_f32_16x16x32_bf16 v[88:91], v[186:189], v[230:233], v[88:91]
	v_mfma_f32_16x16x32_bf16 v[84:87], v[194:197], v[218:221], v[84:87]
	v_mfma_f32_16x16x32_bf16 v[80:83], v[194:197], v[230:233], v[80:83]
	v_mfma_f32_16x16x32_bf16 v[76:79], v[202:205], v[218:221], v[76:79]
	v_mfma_f32_16x16x32_bf16 v[72:75], v[202:205], v[230:233], v[72:75]
	v_mfma_f32_16x16x32_bf16 v[68:71], v[210:213], v[218:221], v[68:71]
	v_mfma_f32_16x16x32_bf16 v[64:67], v[210:213], v[230:233], v[64:67]
	s_setprio 0
	v_readfirstlane_b32 s19, v144
	v_lshl_add_u64 v[240:241], v[222:223], 0, s[14:15]
	s_mov_b32 m0, s19
	v_readfirstlane_b32 s19, v145
	s_barrier
	ds_read_b128 v[182:185], v153 offset:16384
	ds_read_b128 v[186:189], v153 offset:17408
	ds_read_b128 v[190:193], v154 offset:16384
	ds_read_b128 v[194:197], v154 offset:17408
	ds_read_b128 v[198:201], v162 offset:16384
	ds_read_b128 v[202:205], v162 offset:17408
	ds_read_b128 v[206:209], v163 offset:16384
	ds_read_b128 v[210:213], v163 offset:17408
	global_load_lds_dwordx4 v[240:241], off
	v_lshl_add_u64 v[240:241], v[234:235], 0, s[14:15]
	s_mov_b32 m0, s19
	s_nop 0
	global_load_lds_dwordx4 v[240:241], off
	s_barrier
	s_waitcnt lgkmcnt(0)
	s_setprio 1
	v_mfma_f32_16x16x32_bf16 v[60:63], v[182:185], v[166:169], v[60:63]
	v_mfma_f32_16x16x32_bf16 v[56:59], v[182:185], v[174:177], v[56:59]
	v_mfma_f32_16x16x32_bf16 v[52:55], v[190:193], v[166:169], v[52:55]
	v_mfma_f32_16x16x32_bf16 v[48:51], v[190:193], v[174:177], v[48:51]
	v_mfma_f32_16x16x32_bf16 v[44:47], v[198:201], v[166:169], v[44:47]
	v_mfma_f32_16x16x32_bf16 v[40:43], v[198:201], v[174:177], v[40:43]
	v_mfma_f32_16x16x32_bf16 v[36:39], v[206:209], v[166:169], v[36:39]
	v_mfma_f32_16x16x32_bf16 v[32:35], v[206:209], v[174:177], v[32:35]
	v_mfma_f32_16x16x32_bf16 v[60:63], v[186:189], v[170:173], v[60:63]
	v_mfma_f32_16x16x32_bf16 v[56:59], v[186:189], v[178:181], v[56:59]
	v_mfma_f32_16x16x32_bf16 v[52:55], v[194:197], v[170:173], v[52:55]
	v_mfma_f32_16x16x32_bf16 v[48:51], v[194:197], v[178:181], v[48:51]
	v_mfma_f32_16x16x32_bf16 v[44:47], v[202:205], v[170:173], v[44:47]
	v_mfma_f32_16x16x32_bf16 v[40:43], v[202:205], v[178:181], v[40:43]
	v_mfma_f32_16x16x32_bf16 v[36:39], v[210:213], v[170:173], v[36:39]
	v_mfma_f32_16x16x32_bf16 v[32:35], v[210:213], v[178:181], v[32:35]
	s_setprio 0
	s_barrier
	v_readfirstlane_b32 s19, v146
	v_lshl_add_u64 v[166:167], v[236:237], 0, s[16:17]
	s_mov_b32 m0, s19
	v_readfirstlane_b32 s19, v147
	global_load_lds_dwordx4 v[166:167], off
	v_lshl_add_u64 v[166:167], v[238:239], 0, s[16:17]
	s_mov_b32 m0, s19
	s_nop 0
	global_load_lds_dwordx4 v[166:167], off
	s_waitcnt vmcnt(6)
	s_barrier
	s_setprio 1
	v_mfma_f32_16x16x32_bf16 v[28:31], v[182:185], v[214:217], v[28:31]
	v_mfma_f32_16x16x32_bf16 v[24:27], v[182:185], v[226:229], v[24:27]
	v_mfma_f32_16x16x32_bf16 v[20:23], v[190:193], v[214:217], v[20:23]
	v_mfma_f32_16x16x32_bf16 v[16:19], v[190:193], v[226:229], v[16:19]
	v_mfma_f32_16x16x32_bf16 v[12:15], v[198:201], v[214:217], v[12:15]
	v_mfma_f32_16x16x32_bf16 v[8:11], v[198:201], v[226:229], v[8:11]
	v_mfma_f32_16x16x32_bf16 v[4:7], v[206:209], v[214:217], v[4:7]
	v_mfma_f32_16x16x32_bf16 v[0:3], v[206:209], v[226:229], v[0:3]
	v_mfma_f32_16x16x32_bf16 v[28:31], v[186:189], v[218:221], v[28:31]
	v_mfma_f32_16x16x32_bf16 v[24:27], v[186:189], v[230:233], v[24:27]
	v_mfma_f32_16x16x32_bf16 v[20:23], v[194:197], v[218:221], v[20:23]
	v_mfma_f32_16x16x32_bf16 v[16:19], v[194:197], v[230:233], v[16:19]
	v_mfma_f32_16x16x32_bf16 v[12:15], v[202:205], v[218:221], v[12:15]
	v_mfma_f32_16x16x32_bf16 v[8:11], v[202:205], v[230:233], v[8:11]
	v_mfma_f32_16x16x32_bf16 v[4:7], v[210:213], v[218:221], v[4:7]
	v_mfma_f32_16x16x32_bf16 v[0:3], v[210:213], v[230:233], v[0:3]
	s_setprio 0
	s_barrier
	ds_read_b128 v[166:169], v160
	ds_read_b128 v[170:173], v160 offset:1024
	ds_read_b128 v[174:177], v160 offset:2048
	ds_read_b128 v[178:181], v160 offset:3072
	v_readfirstlane_b32 s19, v148
	v_lshl_add_u64 v[214:215], v[222:223], 0, s[20:21]
	s_mov_b32 m0, s19
	v_readfirstlane_b32 s19, v149
	ds_read_b128 v[182:185], v153 offset:32768
	ds_read_b128 v[186:189], v153 offset:33792
	ds_read_b128 v[190:193], v154 offset:32768
	ds_read_b128 v[194:197], v154 offset:33792
	ds_read_b128 v[198:201], v162 offset:32768
	ds_read_b128 v[202:205], v162 offset:33792
	ds_read_b128 v[206:209], v163 offset:32768
	ds_read_b128 v[210:213], v163 offset:33792
	global_load_lds_dwordx4 v[214:215], off
	v_lshl_add_u64 v[214:215], v[234:235], 0, s[20:21]
	s_mov_b32 m0, s19
	s_nop 0
	global_load_lds_dwordx4 v[214:215], off
	s_waitcnt lgkmcnt(8)
	s_barrier
	s_waitcnt lgkmcnt(0)
	s_setprio 1
	v_mfma_f32_16x16x32_bf16 v[124:127], v[182:185], v[166:169], v[124:127]
	v_mfma_f32_16x16x32_bf16 v[120:123], v[182:185], v[174:177], v[120:123]
	v_mfma_f32_16x16x32_bf16 v[116:119], v[190:193], v[166:169], v[116:119]
	v_mfma_f32_16x16x32_bf16 v[112:115], v[190:193], v[174:177], v[112:115]
	v_mfma_f32_16x16x32_bf16 v[108:111], v[198:201], v[166:169], v[108:111]
	v_mfma_f32_16x16x32_bf16 v[104:107], v[198:201], v[174:177], v[104:107]
	v_mfma_f32_16x16x32_bf16 v[100:103], v[206:209], v[166:169], v[100:103]
	v_mfma_f32_16x16x32_bf16 v[96:99], v[206:209], v[174:177], v[96:99]
	v_mfma_f32_16x16x32_bf16 v[124:127], v[186:189], v[170:173], v[124:127]
	v_mfma_f32_16x16x32_bf16 v[120:123], v[186:189], v[178:181], v[120:123]
	v_mfma_f32_16x16x32_bf16 v[116:119], v[194:197], v[170:173], v[116:119]
	v_mfma_f32_16x16x32_bf16 v[112:115], v[194:197], v[178:181], v[112:115]
	v_mfma_f32_16x16x32_bf16 v[108:111], v[202:205], v[170:173], v[108:111]
	v_mfma_f32_16x16x32_bf16 v[104:107], v[202:205], v[178:181], v[104:107]
	v_mfma_f32_16x16x32_bf16 v[100:103], v[210:213], v[170:173], v[100:103]
	v_mfma_f32_16x16x32_bf16 v[96:99], v[210:213], v[178:181], v[96:99]
	s_setprio 0
	s_barrier
	v_readfirstlane_b32 s19, v155
	v_lshl_add_u64 v[240:241], v[236:237], 0, s[22:23]
	s_mov_b32 m0, s19
	v_readfirstlane_b32 s19, v156
	ds_read_b128 v[214:217], v161
	ds_read_b128 v[218:221], v161 offset:1024
	ds_read_b128 v[226:229], v161 offset:2048
	ds_read_b128 v[230:233], v161 offset:3072
	global_load_lds_dwordx4 v[240:241], off
	v_lshl_add_u64 v[240:241], v[238:239], 0, s[22:23]
	s_mov_b32 m0, s19
	s_nop 0
	global_load_lds_dwordx4 v[240:241], off
	s_barrier
	s_waitcnt lgkmcnt(0)
	s_setprio 1
	v_mfma_f32_16x16x32_bf16 v[92:95], v[182:185], v[214:217], v[92:95]
	v_mfma_f32_16x16x32_bf16 v[88:91], v[182:185], v[226:229], v[88:91]
	v_mfma_f32_16x16x32_bf16 v[84:87], v[190:193], v[214:217], v[84:87]
	v_mfma_f32_16x16x32_bf16 v[80:83], v[190:193], v[226:229], v[80:83]
	v_mfma_f32_16x16x32_bf16 v[76:79], v[198:201], v[214:217], v[76:79]
	v_mfma_f32_16x16x32_bf16 v[72:75], v[198:201], v[226:229], v[72:75]
	v_mfma_f32_16x16x32_bf16 v[68:71], v[206:209], v[214:217], v[68:71]
	v_mfma_f32_16x16x32_bf16 v[64:67], v[206:209], v[226:229], v[64:67]
	v_mfma_f32_16x16x32_bf16 v[92:95], v[186:189], v[218:221], v[92:95]
	v_mfma_f32_16x16x32_bf16 v[88:91], v[186:189], v[230:233], v[88:91]
	v_mfma_f32_16x16x32_bf16 v[84:87], v[194:197], v[218:221], v[84:87]
	v_mfma_f32_16x16x32_bf16 v[80:83], v[194:197], v[230:233], v[80:83]
	v_mfma_f32_16x16x32_bf16 v[76:79], v[202:205], v[218:221], v[76:79]
	v_mfma_f32_16x16x32_bf16 v[72:75], v[202:205], v[230:233], v[72:75]
	v_mfma_f32_16x16x32_bf16 v[68:71], v[210:213], v[218:221], v[68:71]
	v_mfma_f32_16x16x32_bf16 v[64:67], v[210:213], v[230:233], v[64:67]
	s_setprio 0
	v_readfirstlane_b32 s19, v150
	v_lshl_add_u64 v[222:223], v[222:223], 0, s[34:35]
	s_mov_b32 m0, s19
	v_readfirstlane_b32 s19, v151
	s_barrier
	ds_read_b128 v[182:185], v153 offset:49152
	ds_read_b128 v[186:189], v153 offset:50176
	ds_read_b128 v[190:193], v154 offset:49152
	ds_read_b128 v[194:197], v154 offset:50176
	ds_read_b128 v[198:201], v162 offset:49152
	ds_read_b128 v[202:205], v162 offset:50176
	ds_read_b128 v[206:209], v163 offset:49152
	ds_read_b128 v[210:213], v163 offset:50176
	global_load_lds_dwordx4 v[222:223], off
	v_lshl_add_u64 v[222:223], v[234:235], 0, s[34:35]
	s_mov_b32 m0, s19
	s_nop 0
	global_load_lds_dwordx4 v[222:223], off
	s_barrier
	s_waitcnt lgkmcnt(0)
	s_setprio 1
	v_mfma_f32_16x16x32_bf16 v[60:63], v[182:185], v[166:169], v[60:63]
	v_mfma_f32_16x16x32_bf16 v[56:59], v[182:185], v[174:177], v[56:59]
	v_mfma_f32_16x16x32_bf16 v[52:55], v[190:193], v[166:169], v[52:55]
	v_mfma_f32_16x16x32_bf16 v[48:51], v[190:193], v[174:177], v[48:51]
	v_mfma_f32_16x16x32_bf16 v[44:47], v[198:201], v[166:169], v[44:47]
	v_mfma_f32_16x16x32_bf16 v[40:43], v[198:201], v[174:177], v[40:43]
	v_mfma_f32_16x16x32_bf16 v[36:39], v[206:209], v[166:169], v[36:39]
	v_mfma_f32_16x16x32_bf16 v[32:35], v[206:209], v[174:177], v[32:35]
	v_mfma_f32_16x16x32_bf16 v[60:63], v[186:189], v[170:173], v[60:63]
	v_mfma_f32_16x16x32_bf16 v[56:59], v[186:189], v[178:181], v[56:59]
	v_mfma_f32_16x16x32_bf16 v[52:55], v[194:197], v[170:173], v[52:55]
	v_mfma_f32_16x16x32_bf16 v[48:51], v[194:197], v[178:181], v[48:51]
	v_mfma_f32_16x16x32_bf16 v[44:47], v[202:205], v[170:173], v[44:47]
	v_mfma_f32_16x16x32_bf16 v[40:43], v[202:205], v[178:181], v[40:43]
	v_mfma_f32_16x16x32_bf16 v[36:39], v[210:213], v[170:173], v[36:39]
	v_mfma_f32_16x16x32_bf16 v[32:35], v[210:213], v[178:181], v[32:35]
	s_setprio 0
	s_barrier
	v_readfirstlane_b32 s19, v157
	v_lshl_add_u64 v[166:167], v[236:237], 0, s[36:37]
	s_mov_b32 m0, s19
	v_readfirstlane_b32 s19, v158
	global_load_lds_dwordx4 v[166:167], off
	v_lshl_add_u64 v[166:167], v[238:239], 0, s[36:37]
	s_mov_b32 m0, s19
	s_nop 0
	global_load_lds_dwordx4 v[166:167], off
	s_waitcnt vmcnt(6)
	s_barrier
	s_setprio 1
	v_mfma_f32_16x16x32_bf16 v[28:31], v[182:185], v[214:217], v[28:31]
	v_mfma_f32_16x16x32_bf16 v[24:27], v[182:185], v[226:229], v[24:27]
	v_mfma_f32_16x16x32_bf16 v[20:23], v[190:193], v[214:217], v[20:23]
	v_mfma_f32_16x16x32_bf16 v[16:19], v[190:193], v[226:229], v[16:19]
	v_mfma_f32_16x16x32_bf16 v[12:15], v[198:201], v[214:217], v[12:15]
	v_mfma_f32_16x16x32_bf16 v[8:11], v[198:201], v[226:229], v[8:11]
	v_mfma_f32_16x16x32_bf16 v[4:7], v[206:209], v[214:217], v[4:7]
	v_mfma_f32_16x16x32_bf16 v[0:3], v[206:209], v[226:229], v[0:3]
	v_mfma_f32_16x16x32_bf16 v[28:31], v[186:189], v[218:221], v[28:31]
	v_mfma_f32_16x16x32_bf16 v[24:27], v[186:189], v[230:233], v[24:27]
	v_mfma_f32_16x16x32_bf16 v[20:23], v[194:197], v[218:221], v[20:23]
	v_mfma_f32_16x16x32_bf16 v[16:19], v[194:197], v[230:233], v[16:19]
	v_mfma_f32_16x16x32_bf16 v[12:15], v[202:205], v[218:221], v[12:15]
	v_mfma_f32_16x16x32_bf16 v[8:11], v[202:205], v[230:233], v[8:11]
	v_mfma_f32_16x16x32_bf16 v[4:7], v[210:213], v[218:221], v[4:7]
	v_mfma_f32_16x16x32_bf16 v[0:3], v[210:213], v[230:233], v[0:3]
	s_setprio 0
	s_add_i32 s18, s18, 2
	s_add_u32 s26, s26, 0x100
	s_addc_u32 s27, s27, 0
	s_cmpk_lt_u32 s18, 0x54
	s_cbranch_scc1 .Lmy_rot_2
	s_barrier
	s_add_u32 s18, s24, 0x2b80
	s_addc_u32 s19, s25, 0
	v_readfirstlane_b32 s24, v164
	v_lshl_add_u64 v[206:207], s[18:19], 0, v[130:131]
	s_mov_b32 m0, s24
	ds_read_b128 v[132:135], v152
	ds_read_b128 v[136:139], v152 offset:1024
	ds_read_b128 v[166:169], v152 offset:2048
	ds_read_b128 v[170:173], v152 offset:3072
	ds_read_b128 v[174:177], v153
	ds_read_b128 v[178:181], v153 offset:1024
	ds_read_b128 v[182:185], v154
	ds_read_b128 v[186:189], v154 offset:1024
	ds_read_b128 v[190:193], v162
	ds_read_b128 v[194:197], v162 offset:1024
	ds_read_b128 v[198:201], v163
	ds_read_b128 v[202:205], v163 offset:1024
	global_load_lds_dwordx4 v[206:207], off
	v_lshl_add_u64 v[206:207], s[18:19], 0, v[128:129]
	v_readfirstlane_b32 s18, v165
	s_mov_b32 m0, s18
	s_nop 0
	global_load_lds_dwordx4 v[206:207], off
	s_barrier
	s_waitcnt lgkmcnt(0)
	s_setprio 1
	v_mfma_f32_16x16x32_bf16 v[124:127], v[174:177], v[132:135], v[124:127]
	v_mfma_f32_16x16x32_bf16 v[120:123], v[174:177], v[166:169], v[120:123]
	v_mfma_f32_16x16x32_bf16 v[116:119], v[182:185], v[132:135], v[116:119]
	v_mfma_f32_16x16x32_bf16 v[112:115], v[182:185], v[166:169], v[112:115]
	v_mfma_f32_16x16x32_bf16 v[124:127], v[178:181], v[136:139], v[124:127]
	v_mfma_f32_16x16x32_bf16 v[120:123], v[178:181], v[170:173], v[120:123]
	v_mfma_f32_16x16x32_bf16 v[116:119], v[186:189], v[136:139], v[116:119]
	v_mfma_f32_16x16x32_bf16 v[112:115], v[186:189], v[170:173], v[112:115]
	v_mfma_f32_16x16x32_bf16 v[108:111], v[190:193], v[132:135], v[108:111]
	v_mfma_f32_16x16x32_bf16 v[104:107], v[190:193], v[166:169], v[104:107]
	v_mfma_f32_16x16x32_bf16 v[100:103], v[198:201], v[132:135], v[100:103]
	v_mfma_f32_16x16x32_bf16 v[96:99], v[198:201], v[166:169], v[96:99]
	v_mfma_f32_16x16x32_bf16 v[206:209], v[194:197], v[136:139], v[108:111]
	v_mfma_f32_16x16x32_bf16 v[210:213], v[194:197], v[170:173], v[104:107]
	v_mfma_f32_16x16x32_bf16 v[214:217], v[202:205], v[136:139], v[100:103]
	v_mfma_f32_16x16x32_bf16 v[218:221], v[202:205], v[170:173], v[96:99]
	s_setprio 0
	s_barrier
	s_nop 1
	ds_read_b128 v[96:99], v159
	ds_read_b128 v[100:103], v159 offset:1024
	ds_read_b128 v[104:107], v159 offset:2048
	ds_read_b128 v[108:111], v159 offset:3072
	s_barrier
	s_waitcnt lgkmcnt(0)
	s_setprio 1
	v_mfma_f32_16x16x32_bf16 v[92:95], v[174:177], v[96:99], v[92:95]
	v_mfma_f32_16x16x32_bf16 v[88:91], v[174:177], v[104:107], v[88:91]
	v_mfma_f32_16x16x32_bf16 v[84:87], v[182:185], v[96:99], v[84:87]
	v_mfma_f32_16x16x32_bf16 v[80:83], v[182:185], v[104:107], v[80:83]
	v_mfma_f32_16x16x32_bf16 v[92:95], v[178:181], v[100:103], v[92:95]
	v_mfma_f32_16x16x32_bf16 v[88:91], v[178:181], v[108:111], v[88:91]
	v_mfma_f32_16x16x32_bf16 v[84:87], v[186:189], v[100:103], v[84:87]
	v_mfma_f32_16x16x32_bf16 v[80:83], v[186:189], v[108:111], v[80:83]
	v_mfma_f32_16x16x32_bf16 v[76:79], v[190:193], v[96:99], v[76:79]
	v_mfma_f32_16x16x32_bf16 v[72:75], v[190:193], v[104:107], v[72:75]
	v_mfma_f32_16x16x32_bf16 v[68:71], v[198:201], v[96:99], v[68:71]
	v_mfma_f32_16x16x32_bf16 v[64:67], v[198:201], v[104:107], v[64:67]
	v_mfma_f32_16x16x32_bf16 v[174:177], v[194:197], v[100:103], v[76:79]
	v_mfma_f32_16x16x32_bf16 v[178:181], v[194:197], v[108:111], v[72:75]
	v_mfma_f32_16x16x32_bf16 v[182:185], v[202:205], v[100:103], v[68:71]
	v_mfma_f32_16x16x32_bf16 v[186:189], v[202:205], v[108:111], v[64:67]
	s_setprio 0
	s_barrier
	s_nop 1
	ds_read_b128 v[64:67], v153 offset:16384
	ds_read_b128 v[68:71], v153 offset:17408
	ds_read_b128 v[72:75], v154 offset:16384
	ds_read_b128 v[76:79], v154 offset:17408
	ds_read_b128 v[190:193], v162 offset:16384
	ds_read_b128 v[194:197], v162 offset:17408
	ds_read_b128 v[198:201], v163 offset:16384
	ds_read_b128 v[202:205], v163 offset:17408
	s_waitcnt vmcnt(4)
	s_barrier
	s_waitcnt lgkmcnt(0)
	s_setprio 1
	v_mfma_f32_16x16x32_bf16 v[60:63], v[64:67], v[132:135], v[60:63]
	v_mfma_f32_16x16x32_bf16 v[56:59], v[64:67], v[166:169], v[56:59]
	v_mfma_f32_16x16x32_bf16 v[52:55], v[72:75], v[132:135], v[52:55]
	v_mfma_f32_16x16x32_bf16 v[48:51], v[72:75], v[166:169], v[48:51]
	v_mfma_f32_16x16x32_bf16 v[60:63], v[68:71], v[136:139], v[60:63]
	v_mfma_f32_16x16x32_bf16 v[56:59], v[68:71], v[170:173], v[56:59]
	v_mfma_f32_16x16x32_bf16 v[52:55], v[76:79], v[136:139], v[52:55]
	v_mfma_f32_16x16x32_bf16 v[48:51], v[76:79], v[170:173], v[48:51]
	v_mfma_f32_16x16x32_bf16 v[44:47], v[190:193], v[132:135], v[44:47]
	v_mfma_f32_16x16x32_bf16 v[40:43], v[190:193], v[166:169], v[40:43]
	v_mfma_f32_16x16x32_bf16 v[36:39], v[198:201], v[132:135], v[36:39]
	v_mfma_f32_16x16x32_bf16 v[32:35], v[198:201], v[166:169], v[32:35]
	v_mfma_f32_16x16x32_bf16 v[226:229], v[194:197], v[136:139], v[44:47]
	v_mfma_f32_16x16x32_bf16 v[230:233], v[194:197], v[170:173], v[40:43]
	v_mfma_f32_16x16x32_bf16 v[132:135], v[202:205], v[136:139], v[36:39]
	v_mfma_f32_16x16x32_bf16 v[136:139], v[202:205], v[170:173], v[32:35]
	s_setprio 0
	s_setprio 1
	v_mfma_f32_16x16x32_bf16 v[28:31], v[64:67], v[96:99], v[28:31]
	v_mfma_f32_16x16x32_bf16 v[24:27], v[64:67], v[104:107], v[24:27]
	v_mfma_f32_16x16x32_bf16 v[20:23], v[72:75], v[96:99], v[20:23]
	v_mfma_f32_16x16x32_bf16 v[16:19], v[72:75], v[104:107], v[16:19]
	v_mfma_f32_16x16x32_bf16 v[28:31], v[68:71], v[100:103], v[28:31]
	v_mfma_f32_16x16x32_bf16 v[24:27], v[68:71], v[108:111], v[24:27]
	v_mfma_f32_16x16x32_bf16 v[20:23], v[76:79], v[100:103], v[20:23]
	v_mfma_f32_16x16x32_bf16 v[16:19], v[76:79], v[108:111], v[16:19]
	v_mfma_f32_16x16x32_bf16 v[12:15], v[190:193], v[96:99], v[12:15]
	v_mfma_f32_16x16x32_bf16 v[8:11], v[190:193], v[104:107], v[8:11]
	v_mfma_f32_16x16x32_bf16 v[4:7], v[198:201], v[96:99], v[4:7]
	v_mfma_f32_16x16x32_bf16 v[0:3], v[198:201], v[104:107], v[0:3]
	v_mfma_f32_16x16x32_bf16 v[164:167], v[194:197], v[100:103], v[12:15]
	v_mfma_f32_16x16x32_bf16 v[168:171], v[194:197], v[108:111], v[8:11]
	v_mfma_f32_16x16x32_bf16 v[190:193], v[202:205], v[100:103], v[4:7]
	v_mfma_f32_16x16x32_bf16 v[194:197], v[202:205], v[108:111], v[0:3]
	s_setprio 0
	s_barrier
	s_nop 1
	ds_read_b128 v[0:3], v160
	ds_read_b128 v[4:7], v160 offset:1024
	ds_read_b128 v[198:201], v160 offset:2048
	ds_read_b128 v[202:205], v160 offset:3072
	ds_read_b128 v[8:11], v153 offset:32768
	ds_read_b128 v[12:15], v153 offset:33792
	ds_read_b128 v[32:35], v154 offset:32768
	ds_read_b128 v[36:39], v154 offset:33792
	ds_read_b128 v[40:43], v162 offset:32768
	ds_read_b128 v[44:47], v162 offset:33792
	ds_read_b128 v[234:237], v163 offset:32768
	ds_read_b128 v[238:241], v163 offset:33792
	s_waitcnt vmcnt(2)
	s_barrier
	s_waitcnt lgkmcnt(0)
	s_setprio 1
	v_mfma_f32_16x16x32_bf16 v[64:67], v[8:11], v[0:3], v[124:127]
	v_mfma_f32_16x16x32_bf16 v[104:107], v[12:15], v[4:7], v[64:67]
	v_mfma_f32_16x16x32_bf16 v[64:67], v[8:11], v[198:201], v[120:123]
	v_mfma_f32_16x16x32_bf16 v[108:111], v[12:15], v[202:205], v[64:67]
	v_mfma_f32_16x16x32_bf16 v[64:67], v[32:35], v[0:3], v[116:119]
	v_mfma_f32_16x16x32_bf16 v[96:99], v[36:39], v[4:7], v[64:67]
	v_mfma_f32_16x16x32_bf16 v[64:67], v[32:35], v[198:201], v[112:115]
	v_mfma_f32_16x16x32_bf16 v[100:103], v[36:39], v[202:205], v[64:67]
	v_mfma_f32_16x16x32_bf16 v[64:67], v[40:43], v[0:3], v[206:209]
	v_mfma_f32_16x16x32_bf16 v[72:75], v[44:47], v[4:7], v[64:67]
	v_mfma_f32_16x16x32_bf16 v[64:67], v[40:43], v[198:201], v[210:213]
	v_mfma_f32_16x16x32_bf16 v[76:79], v[44:47], v[202:205], v[64:67]
	v_mfma_f32_16x16x32_bf16 v[64:67], v[234:237], v[0:3], v[214:217]
	v_mfma_f32_16x16x32_bf16 v[68:71], v[234:237], v[198:201], v[218:221]
	v_mfma_f32_16x16x32_bf16 v[64:67], v[238:241], v[4:7], v[64:67]
	v_mfma_f32_16x16x32_bf16 v[68:71], v[238:241], v[202:205], v[68:71]
	s_setprio 0
	s_barrier
	ds_read_b128 v[206:209], v161
	ds_read_b128 v[210:213], v161 offset:1024
	ds_read_b128 v[214:217], v161 offset:2048
	ds_read_b128 v[218:221], v161 offset:3072
	s_waitcnt vmcnt(0)
	s_barrier
	s_waitcnt lgkmcnt(0)
	s_setprio 1
	v_mfma_f32_16x16x32_bf16 v[92:95], v[8:11], v[206:209], v[92:95]
	v_mfma_f32_16x16x32_bf16 v[8:11], v[8:11], v[214:217], v[88:91]
	v_mfma_f32_16x16x32_bf16 v[124:127], v[12:15], v[218:221], v[8:11]
	v_mfma_f32_16x16x32_bf16 v[8:11], v[32:35], v[206:209], v[84:87]
	v_mfma_f32_16x16x32_bf16 v[112:115], v[36:39], v[210:213], v[8:11]
	v_mfma_f32_16x16x32_bf16 v[8:11], v[32:35], v[214:217], v[80:83]
	v_mfma_f32_16x16x32_bf16 v[116:119], v[36:39], v[218:221], v[8:11]
	v_mfma_f32_16x16x32_bf16 v[8:11], v[40:43], v[206:209], v[174:177]
	v_mfma_f32_16x16x32_bf16 v[88:91], v[44:47], v[210:213], v[8:11]
	v_mfma_f32_16x16x32_bf16 v[8:11], v[40:43], v[214:217], v[178:181]
	v_mfma_f32_16x16x32_bf16 v[120:123], v[12:15], v[210:213], v[92:95]
	v_mfma_f32_16x16x32_bf16 v[92:95], v[44:47], v[218:221], v[8:11]
	v_mfma_f32_16x16x32_bf16 v[8:11], v[234:237], v[206:209], v[182:185]
	v_mfma_f32_16x16x32_bf16 v[80:83], v[238:241], v[210:213], v[8:11]
	v_mfma_f32_16x16x32_bf16 v[8:11], v[234:237], v[214:217], v[186:189]
	v_mfma_f32_16x16x32_bf16 v[84:87], v[238:241], v[218:221], v[8:11]
	s_setprio 0
	s_barrier
	ds_read_b128 v[172:175], v153 offset:49152
	ds_read_b128 v[176:179], v153 offset:50176
	ds_read_b128 v[180:183], v154 offset:49152
	ds_read_b128 v[184:187], v154 offset:50176
	ds_read_b128 v[234:237], v162 offset:49152
	ds_read_b128 v[238:241], v162 offset:50176
	ds_read_b128 v[242:245], v163 offset:49152
	ds_read_b128 v[246:249], v163 offset:50176
	s_barrier
	s_waitcnt lgkmcnt(0)
	s_setprio 1
	v_mfma_f32_16x16x32_bf16 v[8:11], v[172:175], v[0:3], v[60:63]
	v_mfma_f32_16x16x32_bf16 v[40:43], v[176:179], v[4:7], v[8:11]
	v_mfma_f32_16x16x32_bf16 v[8:11], v[172:175], v[198:201], v[56:59]
	v_mfma_f32_16x16x32_bf16 v[44:47], v[176:179], v[202:205], v[8:11]
	v_mfma_f32_16x16x32_bf16 v[8:11], v[180:183], v[0:3], v[52:55]
	v_mfma_f32_16x16x32_bf16 v[32:35], v[184:187], v[4:7], v[8:11]
	v_mfma_f32_16x16x32_bf16 v[8:11], v[180:183], v[198:201], v[48:51]
	v_mfma_f32_16x16x32_bf16 v[36:39], v[184:187], v[202:205], v[8:11]
	v_mfma_f32_16x16x32_bf16 v[8:11], v[234:237], v[0:3], v[226:229]
	v_mfma_f32_16x16x32_bf16 v[0:3], v[242:245], v[0:3], v[132:135]
	v_mfma_f32_16x16x32_bf16 v[8:11], v[238:241], v[4:7], v[8:11]
	v_mfma_f32_16x16x32_bf16 v[12:15], v[234:237], v[198:201], v[230:233]
	v_mfma_f32_16x16x32_bf16 v[0:3], v[246:249], v[4:7], v[0:3]
	v_mfma_f32_16x16x32_bf16 v[4:7], v[242:245], v[198:201], v[136:139]
	v_mfma_f32_16x16x32_bf16 v[12:15], v[238:241], v[202:205], v[12:15]
	v_mfma_f32_16x16x32_bf16 v[4:7], v[246:249], v[202:205], v[4:7]
	s_setprio 0
	s_setprio 1
	v_mfma_f32_16x16x32_bf16 v[16:19], v[180:183], v[214:217], v[16:19]
	v_mfma_f32_16x16x32_bf16 v[24:27], v[172:175], v[214:217], v[24:27]
	v_mfma_f32_16x16x32_bf16 v[52:55], v[184:187], v[218:221], v[16:19]
	v_mfma_f32_16x16x32_bf16 v[16:19], v[234:237], v[206:209], v[164:167]
	v_mfma_f32_16x16x32_bf16 v[28:31], v[172:175], v[206:209], v[28:31]
	v_mfma_f32_16x16x32_bf16 v[60:63], v[176:179], v[218:221], v[24:27]
	v_mfma_f32_16x16x32_bf16 v[20:23], v[180:183], v[206:209], v[20:23]
	v_mfma_f32_16x16x32_bf16 v[24:27], v[238:241], v[210:213], v[16:19]
	v_mfma_f32_16x16x32_bf16 v[16:19], v[234:237], v[214:217], v[168:171]
	v_mfma_f32_16x16x32_bf16 v[56:59], v[176:179], v[210:213], v[28:31]
	v_mfma_f32_16x16x32_bf16 v[48:51], v[184:187], v[210:213], v[20:23]
	v_mfma_f32_16x16x32_bf16 v[28:31], v[238:241], v[218:221], v[16:19]
	v_mfma_f32_16x16x32_bf16 v[16:19], v[242:245], v[206:209], v[190:193]
	v_mfma_f32_16x16x32_bf16 v[20:23], v[242:245], v[214:217], v[194:197]
	v_mfma_f32_16x16x32_bf16 v[16:19], v[246:249], v[210:213], v[16:19]
	v_mfma_f32_16x16x32_bf16 v[20:23], v[246:249], v[218:221], v[20:23]
	s_setprio 0
	s_andn2_b64 vcc, exec, s[4:5]
	s_barrier
	s_cbranch_vccnz .LBB0_1463
	s_barrier
	s_branch .LBB0_1463
